# zpass: hand-written row-per-wave fast path (8-byte lane accesses, 16-lane DPP LayerNorm, 2-row prefetch) on top of v22
# speedup vs baseline: 1.0238x; 1.0108x over previous
; DI int otid() { int t = threadIdx.x; asm volatile("" : "+v"(t)); return t; }
; DI void zpass_phase(const Params& P) {
;     const bf16_t* PL = (const bf16_t*)(P.ws + OFF_PL1); const bf16_t* YF = (const bf16_t*)(P.ws + OFF_YF); const bf16_t* YB = (const bf16_t*)(P.ws + OFF_YB);
;     const float* BON = (const float*)(P.ws + OFF_BONUS); bf16_t* Y = (bf16_t*)(P.ws + OFF_H); const bf16_t* Gt = (const bf16_t*)(P.ws + OFF_G);
;     const int tid = otid(), hw = tid >> 5, i = tid & 31;
;     const int stride = gridDim.x * 8;
;     for (int task0 = blockIdx.x * 8 + hw; task0 < NLAT * 12; task0 += 4 * stride) {
;         unsigned ya[4], yb[4]; float bon[4]; unsigned short vr[4][6];
.LBB0_1187:
	s_or_b64 exec, exec, s[0:1]
	v_mov_b32_e32 v1, v216
	s_barrier
	s_mov_b32 s3, 0xc0000
	v_ashrrev_i32_e32 v0, 5, v1
	v_lshl_add_u32 v18, s2, 3, v0
	v_cmp_gt_i32_e32 vcc, s3, v18
	s_and_saveexec_b64 s[10:11], vcc
	s_cbranch_execz .LBB0_1212
	s_cmpk_eq_i32 s33, 0x200
	s_cbranch_scc1 .Lzp_fast
	v_lshlrev_b32_e32 v1, 1, v1
	v_and_b32_e32 v22, 62, v1
	v_mbcnt_hi_u32_b32 v1, -1, v217
	v_and_b32_e32 v2, 64, v1
	v_add_u32_e32 v2, 64, v2
	v_xor_b32_e32 v3, 16, v1
	v_cmp_lt_i32_e32 vcc, v3, v2
	s_add_u32 s0, s50, 0x23d00000
	s_addc_u32 s1, s51, 0
	v_cndmask_b32_e32 v3, v1, v3, vcc
	v_lshlrev_b32_e32 v23, 2, v3
	v_xor_b32_e32 v3, 8, v1
	v_cmp_lt_i32_e32 vcc, v3, v2
	s_add_u32 s4, s50, 0x29d00000
	s_addc_u32 s5, s51, 0
	v_cndmask_b32_e32 v3, v1, v3, vcc
	v_lshlrev_b32_e32 v24, 2, v3
	v_xor_b32_e32 v3, 4, v1
	v_cmp_lt_i32_e32 vcc, v3, v2
	s_add_u32 s12, s50, 0x30d00000
	v_lshlrev_b32_e32 v0, 6, v0
	v_cndmask_b32_e32 v3, v1, v3, vcc
	v_lshlrev_b32_e32 v25, 2, v3
	v_xor_b32_e32 v3, 2, v1
	v_cmp_lt_i32_e32 vcc, v3, v2
	s_mul_i32 s6, s33, 0x600
	s_addc_u32 s13, s51, 0
	v_cndmask_b32_e32 v3, v1, v3, vcc
	v_lshlrev_b32_e32 v26, 2, v3
	v_xor_b32_e32 v3, 1, v1
	v_cmp_lt_i32_e32 vcc, v3, v2
	s_lshl_b32 s34, s33, 3
	s_lshl_b32 s35, s33, 4
	v_cndmask_b32_e32 v1, v1, v3, vcc
	v_lshlrev_b32_e32 v27, 2, v1
	v_lshl_or_b32 v28, s33, 10, v22
	v_lshl_add_u32 v29, s2, 9, v0
	s_lshl_b32 s36, s33, 11
	s_mul_i32 s37, s33, 24
	s_movk_i32 s42, 0x600
	v_or_b32_e32 v30, s6, v22
	v_lshl_or_b32 v31, s33, 9, v22
	s_mov_b64 s[14:15], 0
	s_mov_b32 s43, 0x2aaaaaab
	s_movk_i32 s44, 0x1fff
	s_movk_i32 s45, 0xfd00
	v_mov_b64_e32 v[0:1], s[0:1]
	v_mov_b64_e32 v[2:3], s[4:5]
	s_mov_b32 s46, 0x300000
	s_movk_i32 s47, 0x1700
	v_mov_b64_e32 v[4:5], s[50:51]
	s_mov_b64 s[16:17], 0xc100c00
	s_movk_i32 s54, 0x1000
	v_mov_b64_e32 v[6:7], s[8:9]
	v_mov_b32_e32 v32, 0x3a27c5ac
	s_mov_b32 s55, 0x800000
	s_mov_b32 s56, 0xbffff
	s_branch .LBB0_1190

; DI void zpass_phase(const Params& P) {
;     ...
;     for (int task0 = blockIdx.x * 8 + hw; task0 < NLAT * 12; task0 += 4 * stride) {
;         unsigned ya[4], yb[4]; float bon[4]; unsigned short vr[4][6];
; #pragma unroll
;         for (int u = 0; u < 4; ++u) {
;             const int task = task0 + u * stride; const bool ok = task < NLAT * 12;
;             const int row = ok ? task / 12 : 0, h = ok ? task - row * 12 : 0, t = row & 8191, c = 64 * h + 2 * i;
;             ya[u] = *(const unsigned*)(YF + (size_t)row * 768 + c); yb[u] = *(const unsigned*)(YB + (size_t)row * 768 + c);
;             bon[u] = BON[(size_t)row * 12 + h] + BON[(size_t)NLAT * 12 + (size_t)row * 12 + h];
;             const bf16_t* pv = PL + (size_t)row * CDIN + 1536 + c;
;             const unsigned cur = *(const unsigned*)pv, prv = t > 0 ? *(const unsigned*)(pv - CDIN) : 0u, nxt = t + 1 < SEQ ? *(const unsigned*)(pv + CDIN) : 0u;
;             vr[u][0] = (unsigned short)(cur & 0xffff); vr[u][1] = (unsigned short)(cur >> 16); vr[u][2] = (unsigned short)(prv & 0xffff); vr[u][3] = (unsigned short)(prv >> 16);
;             vr[u][4] = (unsigned short)(nxt & 0xffff); vr[u][5] = (unsigned short)(nxt >> 16);
;         }
.Lzp_fast:
	v_lshrrev_b32_e32 v176, 6, v216
	v_and_b32_e32 v177, 63, v216
	v_mov_b32_e32 v39, 0x3a27c5ac
	v_readfirstlane_b32 s3, v176
	s_lshl_b32 s6, s2, 2
	v_lshlrev_b32_e32 v36, 3, v177
	v_lshlrev_b32_e32 v38, 4, v177
	v_lshrrev_b32_e32 v37, 4, v177
	s_add_u32 s3, s3, s6
	s_lshl_b32 s3, s3, 5
	s_add_u32 s4, s3, 32
	v_lshlrev_b32_e32 v37, 2, v37
	v_readlane_b32 s74, v251, 19
	v_readlane_b32 s75, v251, 20
	s_add_u32 s60, s50, 0x23d00000
	s_addc_u32 s61, s51, 0
	s_add_u32 s62, s50, 0x29d00000
	s_addc_u32 s63, s51, 0
	s_add_u32 s64, s50, 0x31900000
	s_addc_u32 s65, s51, 0
	s_add_u32 s66, s50, 0xc100c00
	s_addc_u32 s67, s51, 0
	s_add_u32 s68, s50, 0x30d00000
	s_addc_u32 s69, s51, 0
	s_add_u32 s70, s50, 0x31000000
	s_addc_u32 s71, s51, 0
	s_add_u32 s74, s74, 0x1800
	s_addc_u32 s75, s75, 0
	global_load_dwordx4 v[0:3], v38, s[74:75]
	global_load_dwordx4 v[4:7], v38, s[38:39]
	global_load_dwordx4 v[8:11], v38, s[40:41]
	global_load_dwordx4 v[12:15], v38, s[74:75] offset:1024
	global_load_dwordx4 v[16:19], v38, s[38:39] offset:1024
	global_load_dwordx4 v[20:23], v38, s[40:41] offset:1024
	global_load_dwordx4 v[24:27], v38, s[74:75] offset:2048
	global_load_dwordx4 v[28:31], v38, s[38:39] offset:2048
	global_load_dwordx4 v[32:35], v38, s[40:41] offset:2048
	s_mov_b32 s15, s3
	s_mul_i32 s6, s15, 0x600
	s_add_u32 s72, s60, s6
	s_addc_u32 s73, s61, 0
	global_load_dwordx2 v[40:41], v36, s[72:73]
	global_load_dwordx2 v[54:55], v36, s[72:73] offset:512
	global_load_dwordx2 v[68:69], v36, s[72:73] offset:1024
	s_add_u32 s72, s62, s6
	s_addc_u32 s73, s63, 0
	global_load_dwordx2 v[42:43], v36, s[72:73]
	global_load_dwordx2 v[56:57], v36, s[72:73] offset:512
	global_load_dwordx2 v[70:71], v36, s[72:73] offset:1024
	s_add_u32 s72, s64, s6
	s_addc_u32 s73, s65, 0
	global_load_dwordx2 v[44:45], v36, s[72:73]
	global_load_dwordx2 v[58:59], v36, s[72:73] offset:512
	global_load_dwordx2 v[72:73], v36, s[72:73] offset:1024
	s_mul_i32 s6, s15, 0x1700
	s_add_u32 s72, s66, s6
	s_addc_u32 s73, s67, 0
	global_load_dwordx2 v[46:47], v36, s[72:73]
	global_load_dwordx2 v[60:61], v36, s[72:73] offset:512
	global_load_dwordx2 v[74:75], v36, s[72:73] offset:1024
	s_and_b32 s14, s15, 0x1fff
	s_cmp_lg_u32 s14, 0
	s_cselect_b32 s14, 0x1700, 0
	s_sub_u32 s74, s72, s14
	s_subb_u32 s75, s73, 0
	global_load_dwordx2 v[48:49], v36, s[74:75]
	global_load_dwordx2 v[62:63], v36, s[74:75] offset:512
	global_load_dwordx2 v[76:77], v36, s[74:75] offset:1024
	s_and_b32 s14, s15, 0x1fff
	s_cmp_lg_u32 s14, 0x1fff
	s_cselect_b32 s14, 0x1700, 0
	s_add_u32 s74, s72, s14
	s_addc_u32 s75, s73, 0
	global_load_dwordx2 v[50:51], v36, s[74:75]
	global_load_dwordx2 v[64:65], v36, s[74:75] offset:512
	global_load_dwordx2 v[78:79], v36, s[74:75] offset:1024
	s_mul_i32 s6, s15, 48
	s_add_u32 s72, s68, s6
	s_addc_u32 s73, s69, 0
	global_load_dword v52, v37, s[72:73]
	global_load_dword v66, v37, s[72:73] offset:16
	global_load_dword v80, v37, s[72:73] offset:32
	s_add_u32 s72, s70, s6
	s_addc_u32 s73, s71, 0
	global_load_dword v53, v37, s[72:73]
	global_load_dword v67, v37, s[72:73] offset:16
	global_load_dword v81, v37, s[72:73] offset:32
	s_add_u32 s15, s3, 1
	s_mul_i32 s6, s15, 0x600
	s_add_u32 s72, s60, s6
	s_addc_u32 s73, s61, 0
	global_load_dwordx2 v[84:85], v36, s[72:73]
	global_load_dwordx2 v[98:99], v36, s[72:73] offset:512
	global_load_dwordx2 v[112:113], v36, s[72:73] offset:1024
	s_add_u32 s72, s62, s6
	s_addc_u32 s73, s63, 0
	global_load_dwordx2 v[86:87], v36, s[72:73]
	global_load_dwordx2 v[100:101], v36, s[72:73] offset:512
	global_load_dwordx2 v[114:115], v36, s[72:73] offset:1024
	s_add_u32 s72, s64, s6
	s_addc_u32 s73, s65, 0
	global_load_dwordx2 v[88:89], v36, s[72:73]
	global_load_dwordx2 v[102:103], v36, s[72:73] offset:512
	global_load_dwordx2 v[116:117], v36, s[72:73] offset:1024
	s_mul_i32 s6, s15, 0x1700
	s_add_u32 s72, s66, s6
	s_addc_u32 s73, s67, 0
	global_load_dwordx2 v[90:91], v36, s[72:73]
	global_load_dwordx2 v[104:105], v36, s[72:73] offset:512
	global_load_dwordx2 v[118:119], v36, s[72:73] offset:1024
	s_and_b32 s14, s15, 0x1fff
	s_cmp_lg_u32 s14, 0
	s_cselect_b32 s14, 0x1700, 0
	s_sub_u32 s74, s72, s14
	s_subb_u32 s75, s73, 0
	global_load_dwordx2 v[92:93], v36, s[74:75]
	global_load_dwordx2 v[106:107], v36, s[74:75] offset:512
	global_load_dwordx2 v[120:121], v36, s[74:75] offset:1024
	s_and_b32 s14, s15, 0x1fff
	s_cmp_lg_u32 s14, 0x1fff
	s_cselect_b32 s14, 0x1700, 0
	s_add_u32 s74, s72, s14
	s_addc_u32 s75, s73, 0
	global_load_dwordx2 v[94:95], v36, s[74:75]
	global_load_dwordx2 v[108:109], v36, s[74:75] offset:512
	global_load_dwordx2 v[122:123], v36, s[74:75] offset:1024
	s_mul_i32 s6, s15, 48
	s_add_u32 s72, s68, s6
	s_addc_u32 s73, s69, 0
	global_load_dword v96, v37, s[72:73]
	global_load_dword v110, v37, s[72:73] offset:16
	global_load_dword v124, v37, s[72:73] offset:32
	s_add_u32 s72, s70, s6
	s_addc_u32 s73, s71, 0
	global_load_dword v97, v37, s[72:73]
	global_load_dword v111, v37, s[72:73] offset:16
	global_load_dword v125, v37, s[72:73] offset:32
	s_mov_b32 s5, 10
; DI void zpass_phase(const Params& P) {
;     ...
;         for (int u = 0; u < 4; ++u) {
;             const int task = task0 + u * stride; const bool ok = task < NLAT * 12;
;             const int row = ok ? task / 12 : 0, h = ok ? task - row * 12 : 0, t = row & 8191, c = 64 * h + 2 * i;
;             ya[u] = *(const unsigned*)(YF + (size_t)row * 768 + c); yb[u] = *(const unsigned*)(YB + (size_t)row * 768 + c);
;             bon[u] = BON[(size_t)row * 12 + h] + BON[(size_t)NLAT * 12 + (size_t)row * 12 + h];
;             const bf16_t* pv = PL + (size_t)row * CDIN + 1536 + c;
;             const unsigned cur = *(const unsigned*)pv, prv = t > 0 ? *(const unsigned*)(pv - CDIN) : 0u, nxt = t + 1 < SEQ ? *(const unsigned*)(pv + CDIN) : 0u;
;             vr[u][0] = (unsigned short)(cur & 0xffff); vr[u][1] = (unsigned short)(cur >> 16); vr[u][2] = (unsigned short)(prv & 0xffff); vr[u][3] = (unsigned short)(prv >> 16);
;             vr[u][4] = (unsigned short)(nxt & 0xffff); vr[u][5] = (unsigned short)(nxt >> 16);
;         }
; #pragma unroll
;         for (int u = 0; u < 4; ++u) {
;             const int task = task0 + u * stride; const bool ok = task < NLAT * 12;
;             const int row = ok ? task / 12 : 0, h = ok ? task - row * 12 : 0, c = 64 * h + 2 * i;
;             const float y0 = lo16(ya[u]) + lo16(yb[u]), y1 = hi16(ya[u]) + hi16(yb[u]);
;             float sm = y0 + y1;
; #pragma unroll
;             for (int o = 16; o > 0; o >>= 1) sm += __shfl_xor(sm, o);
;             const float mean = sm * (1.0f / 64.0f); const float d0 = y0 - mean, d1 = y1 - mean;
;             float vs = d0 * d0 + d1 * d1;
; #pragma unroll
;             for (int o = 16; o > 0; o >>= 1) vs += __shfl_xor(vs, o);
;             const float rs = rsqrtf(vs * (1.0f / 64.0f) + LNX_EPS);
;             const float x0 = bf2f(vr[u][0]), x1 = bf2f(vr[u][1]);
;             const float v0 = x0 + (0.5f * (bf2f(vr[u][2]) + bf2f(vr[u][4])) - x0) * P.cd_mu[1536 + c], v1 = x1 + (0.5f * (bf2f(vr[u][3]) + bf2f(vr[u][5])) - x1) * P.cd_mu[1536 + c + 1];
;             const float z0 = d0 * rs * P.cd_lnx_w[c] + P.cd_lnx_b[c] + bon[u] * v0, z1 = d1 * rs * P.cd_lnx_w[c + 1] + P.cd_lnx_b[c + 1] + bon[u] * v1;
;             const unsigned gg = *(const unsigned*)(Gt + (size_t)row * 768 + c);
;             if (ok) *(unsigned*)(Y + (size_t)row * DM + c) = pk2(z0 * lo16(gg), z1 * hi16(gg));
.Lzp_loop:
	s_waitcnt vmcnt(24)
	s_sub_u32 s14, s4, 1
	s_add_u32 s6, s3, 2
	s_min_u32 s15, s6, s14
	s_mul_i32 s6, s15, 0x600
	s_add_u32 s72, s60, s6
	s_addc_u32 s73, s61, 0
	global_load_dwordx2 v[128:129], v36, s[72:73]
	global_load_dwordx2 v[142:143], v36, s[72:73] offset:512
	global_load_dwordx2 v[156:157], v36, s[72:73] offset:1024
	s_add_u32 s72, s62, s6
	s_addc_u32 s73, s63, 0
	global_load_dwordx2 v[130:131], v36, s[72:73]
	global_load_dwordx2 v[144:145], v36, s[72:73] offset:512
	global_load_dwordx2 v[158:159], v36, s[72:73] offset:1024
	s_add_u32 s72, s64, s6
	s_addc_u32 s73, s65, 0
	global_load_dwordx2 v[132:133], v36, s[72:73]
	global_load_dwordx2 v[146:147], v36, s[72:73] offset:512
	global_load_dwordx2 v[160:161], v36, s[72:73] offset:1024
	s_mul_i32 s6, s15, 0x1700
	s_add_u32 s72, s66, s6
	s_addc_u32 s73, s67, 0
	global_load_dwordx2 v[134:135], v36, s[72:73]
	global_load_dwordx2 v[148:149], v36, s[72:73] offset:512
	global_load_dwordx2 v[162:163], v36, s[72:73] offset:1024
	s_and_b32 s14, s15, 0x1fff
	s_cmp_lg_u32 s14, 0
	s_cselect_b32 s14, 0x1700, 0
	s_sub_u32 s74, s72, s14
	s_subb_u32 s75, s73, 0
	global_load_dwordx2 v[136:137], v36, s[74:75]
	global_load_dwordx2 v[150:151], v36, s[74:75] offset:512
	global_load_dwordx2 v[164:165], v36, s[74:75] offset:1024
	s_and_b32 s14, s15, 0x1fff
	s_cmp_lg_u32 s14, 0x1fff
	s_cselect_b32 s14, 0x1700, 0
	s_add_u32 s74, s72, s14
	s_addc_u32 s75, s73, 0
	global_load_dwordx2 v[138:139], v36, s[74:75]
	global_load_dwordx2 v[152:153], v36, s[74:75] offset:512
	global_load_dwordx2 v[166:167], v36, s[74:75] offset:1024
	s_mul_i32 s6, s15, 48
	s_add_u32 s72, s68, s6
	s_addc_u32 s73, s69, 0
	global_load_dword v140, v37, s[72:73]
	global_load_dword v154, v37, s[72:73] offset:16
	global_load_dword v168, v37, s[72:73] offset:32
	s_add_u32 s72, s70, s6
	s_addc_u32 s73, s71, 0
	global_load_dword v141, v37, s[72:73]
	global_load_dword v155, v37, s[72:73] offset:16
	global_load_dword v169, v37, s[72:73] offset:32
	s_and_b32 s14, s3, 0x1fff
	s_cmp_lg_u32 s14, 0
	s_cselect_b32 s12, -1, 0
	s_cmp_lg_u32 s14, 0x1fff
	s_cselect_b32 s13, -1, 0
	s_lshl_b32 s6, s3, 11
	s_add_u32 s72, s24, s6
	s_addc_u32 s73, s25, 0
	v_lshlrev_b32_e32 v180, 16, v40
	v_lshlrev_b32_e32 v181, 16, v42
	v_add_f32_e32 v176, v180, v181
	v_and_b32_e32 v180, 0xffff0000, v40
	v_and_b32_e32 v181, 0xffff0000, v42
	v_add_f32_e32 v177, v180, v181
	v_lshlrev_b32_e32 v180, 16, v41
	v_lshlrev_b32_e32 v181, 16, v43
	v_add_f32_e32 v178, v180, v181
	v_and_b32_e32 v180, 0xffff0000, v41
	v_and_b32_e32 v181, 0xffff0000, v43
	v_add_f32_e32 v179, v180, v181
	v_add_f32_e32 v182, v176, v177
	v_add_f32_e32 v182, v182, v178
	v_add_f32_e32 v182, v182, v179
	s_nop 1
	v_add_f32_dpp v182, v182, v182 quad_perm:[1,0,3,2] row_mask:0xf bank_mask:0xf
	s_nop 1
	v_add_f32_dpp v182, v182, v182 quad_perm:[2,3,0,1] row_mask:0xf bank_mask:0xf
	s_nop 1
	v_add_f32_dpp v182, v182, v182 row_half_mirror row_mask:0xf bank_mask:0xf
	s_nop 1
	v_add_f32_dpp v182, v182, v182 row_mirror row_mask:0xf bank_mask:0xf
	s_nop 0
	v_mul_f32_e32 v183, 0x3c800000, v182
	v_sub_f32_e32 v176, v176, v183
	v_sub_f32_e32 v177, v177, v183
	v_sub_f32_e32 v178, v178, v183
	v_sub_f32_e32 v179, v179, v183
	v_mul_f32_e32 v182, v176, v176
	v_fmac_f32_e32 v182, v177, v177
	v_fmac_f32_e32 v182, v178, v178
	v_fmac_f32_e32 v182, v179, v179
	s_nop 1
	v_add_f32_dpp v182, v182, v182 quad_perm:[1,0,3,2] row_mask:0xf bank_mask:0xf
	s_nop 1
	v_add_f32_dpp v182, v182, v182 quad_perm:[2,3,0,1] row_mask:0xf bank_mask:0xf
	s_nop 1
	v_add_f32_dpp v182, v182, v182 row_half_mirror row_mask:0xf bank_mask:0xf
	s_nop 1
	v_add_f32_dpp v182, v182, v182 row_mirror row_mask:0xf bank_mask:0xf
	s_nop 0
	v_fmamk_f32 v184, v182, 0x3c800000, v39
	v_rsq_f32_e32 v184, v184
	v_and_b32_e32 v48, s12, v48
	v_and_b32_e32 v50, s13, v50
	v_lshlrev_b32_e32 v180, 16, v46
	v_lshlrev_b32_e32 v190, 16, v48
	v_lshlrev_b32_e32 v191, 16, v50
	v_add_f32_e32 v190, v190, v191
	v_fma_f32 v190, 0.5, v190, -v180
	v_fma_f32 v186, v190, v0, v180
	v_and_b32_e32 v180, 0xffff0000, v46
	v_and_b32_e32 v190, 0xffff0000, v48
	v_and_b32_e32 v191, 0xffff0000, v50
	v_add_f32_e32 v190, v190, v191
	v_fma_f32 v190, 0.5, v190, -v180
	v_fma_f32 v187, v190, v1, v180
	v_and_b32_e32 v49, s12, v49
	v_and_b32_e32 v51, s13, v51
	v_lshlrev_b32_e32 v180, 16, v47
	v_lshlrev_b32_e32 v190, 16, v49
	v_lshlrev_b32_e32 v191, 16, v51
	v_add_f32_e32 v190, v190, v191
	v_fma_f32 v190, 0.5, v190, -v180
	v_fma_f32 v188, v190, v2, v180
	v_and_b32_e32 v180, 0xffff0000, v47
	v_and_b32_e32 v190, 0xffff0000, v49
	v_and_b32_e32 v191, 0xffff0000, v51
	v_add_f32_e32 v190, v190, v191
	v_fma_f32 v190, 0.5, v190, -v180
	v_fma_f32 v189, v190, v3, v180
	v_add_f32_e32 v185, v52, v53
	v_mul_f32_e32 v176, v176, v184
	v_fma_f32 v176, v176, v4, v8
	v_fmac_f32_e32 v176, v185, v186
	v_mul_f32_e32 v177, v177, v184
	v_fma_f32 v177, v177, v5, v9
	v_fmac_f32_e32 v177, v185, v187
	v_mul_f32_e32 v178, v178, v184
	v_fma_f32 v178, v178, v6, v10
	v_fmac_f32_e32 v178, v185, v188
	v_mul_f32_e32 v179, v179, v184
	v_fma_f32 v179, v179, v7, v11
	v_fmac_f32_e32 v179, v185, v189
	v_lshlrev_b32_e32 v180, 16, v44
	v_mul_f32_e32 v176, v176, v180
	v_and_b32_e32 v180, 0xffff0000, v44
	v_mul_f32_e32 v177, v177, v180
	v_lshlrev_b32_e32 v180, 16, v45
	v_mul_f32_e32 v178, v178, v180
	v_and_b32_e32 v180, 0xffff0000, v45
	v_mul_f32_e32 v179, v179, v180
	v_cvt_pk_bf16_f32 v192, v176, v177
	v_cvt_pk_bf16_f32 v193, v178, v179
	global_store_dwordx2 v36, v[192:193], s[72:73]
	v_lshlrev_b32_e32 v180, 16, v54
	v_lshlrev_b32_e32 v181, 16, v56
	v_add_f32_e32 v176, v180, v181
	v_and_b32_e32 v180, 0xffff0000, v54
	v_and_b32_e32 v181, 0xffff0000, v56
; DI float bf2f(bf16_t b) { return __uint_as_float(((unsigned)b) << 16); }
; DI unsigned pk2(float lo, float hi) { const f32x2 v = {lo, hi}; return __builtin_bit_cast(unsigned, __builtin_convertvector(v, bf16x2v)); }
; DI float lo16(unsigned u) { return __uint_as_float(u << 16); }
; DI float hi16(unsigned u) { return __uint_as_float(u & 0xffff0000u); }
; DI void zpass_phase(const Params& P) {
;     ...
;         for (int u = 0; u < 4; ++u) {
;             const int task = task0 + u * stride; const bool ok = task < NLAT * 12;
;             const int row = ok ? task / 12 : 0, h = ok ? task - row * 12 : 0, c = 64 * h + 2 * i;
;             const float y0 = lo16(ya[u]) + lo16(yb[u]), y1 = hi16(ya[u]) + hi16(yb[u]);
;             float sm = y0 + y1;
; #pragma unroll
;             for (int o = 16; o > 0; o >>= 1) sm += __shfl_xor(sm, o);
;             const float mean = sm * (1.0f / 64.0f); const float d0 = y0 - mean, d1 = y1 - mean;
;             float vs = d0 * d0 + d1 * d1;
; #pragma unroll
;             for (int o = 16; o > 0; o >>= 1) vs += __shfl_xor(vs, o);
;             const float rs = rsqrtf(vs * (1.0f / 64.0f) + LNX_EPS);
;             const float x0 = bf2f(vr[u][0]), x1 = bf2f(vr[u][1]);
;             const float v0 = x0 + (0.5f * (bf2f(vr[u][2]) + bf2f(vr[u][4])) - x0) * P.cd_mu[1536 + c], v1 = x1 + (0.5f * (bf2f(vr[u][3]) + bf2f(vr[u][5])) - x1) * P.cd_mu[1536 + c + 1];
;             const float z0 = d0 * rs * P.cd_lnx_w[c] + P.cd_lnx_b[c] + bon[u] * v0, z1 = d1 * rs * P.cd_lnx_w[c + 1] + P.cd_lnx_b[c + 1] + bon[u] * v1;
;             const unsigned gg = *(const unsigned*)(Gt + (size_t)row * 768 + c);
;             if (ok) *(unsigned*)(Y + (size_t)row * DM + c) = pk2(z0 * lo16(gg), z1 * hi16(gg));
;         }
	v_add_f32_e32 v177, v180, v181
	v_lshlrev_b32_e32 v180, 16, v55
	v_lshlrev_b32_e32 v181, 16, v57
	v_add_f32_e32 v178, v180, v181
	v_and_b32_e32 v180, 0xffff0000, v55
	v_and_b32_e32 v181, 0xffff0000, v57
	v_add_f32_e32 v179, v180, v181
	v_add_f32_e32 v182, v176, v177
	v_add_f32_e32 v182, v182, v178
	v_add_f32_e32 v182, v182, v179
	s_nop 1
	v_add_f32_dpp v182, v182, v182 quad_perm:[1,0,3,2] row_mask:0xf bank_mask:0xf
	s_nop 1
	v_add_f32_dpp v182, v182, v182 quad_perm:[2,3,0,1] row_mask:0xf bank_mask:0xf
	s_nop 1
	v_add_f32_dpp v182, v182, v182 row_half_mirror row_mask:0xf bank_mask:0xf
	s_nop 1
	v_add_f32_dpp v182, v182, v182 row_mirror row_mask:0xf bank_mask:0xf
	s_nop 0
	v_mul_f32_e32 v183, 0x3c800000, v182
	v_sub_f32_e32 v176, v176, v183
	v_sub_f32_e32 v177, v177, v183
	v_sub_f32_e32 v178, v178, v183
	v_sub_f32_e32 v179, v179, v183
	v_mul_f32_e32 v182, v176, v176
	v_fmac_f32_e32 v182, v177, v177
	v_fmac_f32_e32 v182, v178, v178
	v_fmac_f32_e32 v182, v179, v179
	s_nop 1
	v_add_f32_dpp v182, v182, v182 quad_perm:[1,0,3,2] row_mask:0xf bank_mask:0xf
	s_nop 1
	v_add_f32_dpp v182, v182, v182 quad_perm:[2,3,0,1] row_mask:0xf bank_mask:0xf
	s_nop 1
	v_add_f32_dpp v182, v182, v182 row_half_mirror row_mask:0xf bank_mask:0xf
	s_nop 1
	v_add_f32_dpp v182, v182, v182 row_mirror row_mask:0xf bank_mask:0xf
	s_nop 0
	v_fmamk_f32 v184, v182, 0x3c800000, v39
	v_rsq_f32_e32 v184, v184
	v_and_b32_e32 v62, s12, v62
	v_and_b32_e32 v64, s13, v64
	v_lshlrev_b32_e32 v180, 16, v60
	v_lshlrev_b32_e32 v190, 16, v62
	v_lshlrev_b32_e32 v191, 16, v64
	v_add_f32_e32 v190, v190, v191
	v_fma_f32 v190, 0.5, v190, -v180
	v_fma_f32 v186, v190, v12, v180
	v_and_b32_e32 v180, 0xffff0000, v60
	v_and_b32_e32 v190, 0xffff0000, v62
	v_and_b32_e32 v191, 0xffff0000, v64
	v_add_f32_e32 v190, v190, v191
	v_fma_f32 v190, 0.5, v190, -v180
	v_fma_f32 v187, v190, v13, v180
	v_and_b32_e32 v63, s12, v63
	v_and_b32_e32 v65, s13, v65
	v_lshlrev_b32_e32 v180, 16, v61
	v_lshlrev_b32_e32 v190, 16, v63
	v_lshlrev_b32_e32 v191, 16, v65
	v_add_f32_e32 v190, v190, v191
	v_fma_f32 v190, 0.5, v190, -v180
	v_fma_f32 v188, v190, v14, v180
	v_and_b32_e32 v180, 0xffff0000, v61
	v_and_b32_e32 v190, 0xffff0000, v63
	v_and_b32_e32 v191, 0xffff0000, v65
	v_add_f32_e32 v190, v190, v191
	v_fma_f32 v190, 0.5, v190, -v180
	v_fma_f32 v189, v190, v15, v180
	v_add_f32_e32 v185, v66, v67
	v_mul_f32_e32 v176, v176, v184
	v_fma_f32 v176, v176, v16, v20
	v_fmac_f32_e32 v176, v185, v186
	v_mul_f32_e32 v177, v177, v184
	v_fma_f32 v177, v177, v17, v21
	v_fmac_f32_e32 v177, v185, v187
	v_mul_f32_e32 v178, v178, v184
	v_fma_f32 v178, v178, v18, v22
	v_fmac_f32_e32 v178, v185, v188
	v_mul_f32_e32 v179, v179, v184
	v_fma_f32 v179, v179, v19, v23
	v_fmac_f32_e32 v179, v185, v189
	v_lshlrev_b32_e32 v180, 16, v58
	v_mul_f32_e32 v176, v176, v180
	v_and_b32_e32 v180, 0xffff0000, v58
	v_mul_f32_e32 v177, v177, v180
	v_lshlrev_b32_e32 v180, 16, v59
	v_mul_f32_e32 v178, v178, v180
	v_and_b32_e32 v180, 0xffff0000, v59
	v_mul_f32_e32 v179, v179, v180
	v_cvt_pk_bf16_f32 v194, v176, v177
	v_cvt_pk_bf16_f32 v195, v178, v179
	global_store_dwordx2 v36, v[194:195], s[72:73] offset:512
	v_lshlrev_b32_e32 v180, 16, v68
	v_lshlrev_b32_e32 v181, 16, v70
	v_add_f32_e32 v176, v180, v181
	v_and_b32_e32 v180, 0xffff0000, v68
	v_and_b32_e32 v181, 0xffff0000, v70
	v_add_f32_e32 v177, v180, v181
	v_lshlrev_b32_e32 v180, 16, v69
	v_lshlrev_b32_e32 v181, 16, v71
	v_add_f32_e32 v178, v180, v181
	v_and_b32_e32 v180, 0xffff0000, v69
	v_and_b32_e32 v181, 0xffff0000, v71
	v_add_f32_e32 v179, v180, v181
	v_add_f32_e32 v182, v176, v177
	v_add_f32_e32 v182, v182, v178
	v_add_f32_e32 v182, v182, v179
	s_nop 1
	v_add_f32_dpp v182, v182, v182 quad_perm:[1,0,3,2] row_mask:0xf bank_mask:0xf
	s_nop 1
	v_add_f32_dpp v182, v182, v182 quad_perm:[2,3,0,1] row_mask:0xf bank_mask:0xf
	s_nop 1
	v_add_f32_dpp v182, v182, v182 row_half_mirror row_mask:0xf bank_mask:0xf
	s_nop 1
	v_add_f32_dpp v182, v182, v182 row_mirror row_mask:0xf bank_mask:0xf
	s_nop 0
	v_mul_f32_e32 v183, 0x3c800000, v182
	v_sub_f32_e32 v176, v176, v183
	v_sub_f32_e32 v177, v177, v183
	v_sub_f32_e32 v178, v178, v183
	v_sub_f32_e32 v179, v179, v183
	v_mul_f32_e32 v182, v176, v176
	v_fmac_f32_e32 v182, v177, v177
	v_fmac_f32_e32 v182, v178, v178
	v_fmac_f32_e32 v182, v179, v179
	s_nop 1
	v_add_f32_dpp v182, v182, v182 quad_perm:[1,0,3,2] row_mask:0xf bank_mask:0xf
	s_nop 1
	v_add_f32_dpp v182, v182, v182 quad_perm:[2,3,0,1] row_mask:0xf bank_mask:0xf
	s_nop 1
	v_add_f32_dpp v182, v182, v182 row_half_mirror row_mask:0xf bank_mask:0xf
	s_nop 1
	v_add_f32_dpp v182, v182, v182 row_mirror row_mask:0xf bank_mask:0xf
	s_nop 0
	v_fmamk_f32 v184, v182, 0x3c800000, v39
	v_rsq_f32_e32 v184, v184
	v_and_b32_e32 v76, s12, v76
	v_and_b32_e32 v78, s13, v78
	v_lshlrev_b32_e32 v180, 16, v74
	v_lshlrev_b32_e32 v190, 16, v76
	v_lshlrev_b32_e32 v191, 16, v78
	v_add_f32_e32 v190, v190, v191
	v_fma_f32 v190, 0.5, v190, -v180
	v_fma_f32 v186, v190, v24, v180
	v_and_b32_e32 v180, 0xffff0000, v74
	v_and_b32_e32 v190, 0xffff0000, v76
	v_and_b32_e32 v191, 0xffff0000, v78
	v_add_f32_e32 v190, v190, v191
	v_fma_f32 v190, 0.5, v190, -v180
	v_fma_f32 v187, v190, v25, v180
	v_and_b32_e32 v77, s12, v77
	v_and_b32_e32 v79, s13, v79
	v_lshlrev_b32_e32 v180, 16, v75
	v_lshlrev_b32_e32 v190, 16, v77
	v_lshlrev_b32_e32 v191, 16, v79
	v_add_f32_e32 v190, v190, v191
	v_fma_f32 v190, 0.5, v190, -v180
	v_fma_f32 v188, v190, v26, v180
	v_and_b32_e32 v180, 0xffff0000, v75
	v_and_b32_e32 v190, 0xffff0000, v77
	v_and_b32_e32 v191, 0xffff0000, v79
	v_add_f32_e32 v190, v190, v191
	v_fma_f32 v190, 0.5, v190, -v180
	v_fma_f32 v189, v190, v27, v180
	v_add_f32_e32 v185, v80, v81
	v_mul_f32_e32 v176, v176, v184
	v_fma_f32 v176, v176, v28, v32
	v_fmac_f32_e32 v176, v185, v186
	v_mul_f32_e32 v177, v177, v184
	v_fma_f32 v177, v177, v29, v33
	v_fmac_f32_e32 v177, v185, v187
	v_mul_f32_e32 v178, v178, v184
	v_fma_f32 v178, v178, v30, v34
	v_fmac_f32_e32 v178, v185, v188
	v_mul_f32_e32 v179, v179, v184
	v_fma_f32 v179, v179, v31, v35
	v_fmac_f32_e32 v179, v185, v189
	v_lshlrev_b32_e32 v180, 16, v72
	v_mul_f32_e32 v176, v176, v180
	v_and_b32_e32 v180, 0xffff0000, v72
	v_mul_f32_e32 v177, v177, v180
	v_lshlrev_b32_e32 v180, 16, v73
	v_mul_f32_e32 v178, v178, v180
	v_and_b32_e32 v180, 0xffff0000, v73
	v_mul_f32_e32 v179, v179, v180
	v_cvt_pk_bf16_f32 v196, v176, v177
	v_cvt_pk_bf16_f32 v197, v178, v179
	global_store_dwordx2 v36, v[196:197], s[72:73] offset:1024
	s_add_u32 s3, s3, 1
	s_waitcnt vmcnt(24)
; DI void zpass_phase(const Params& P) {
;     ...
; #pragma unroll
;         for (int u = 0; u < 4; ++u) {
;             const int task = task0 + u * stride; const bool ok = task < NLAT * 12;
;             const int row = ok ? task / 12 : 0, h = ok ? task - row * 12 : 0, t = row & 8191, c = 64 * h + 2 * i;
;             ya[u] = *(const unsigned*)(YF + (size_t)row * 768 + c); yb[u] = *(const unsigned*)(YB + (size_t)row * 768 + c);
;             bon[u] = BON[(size_t)row * 12 + h] + BON[(size_t)NLAT * 12 + (size_t)row * 12 + h];
;             const bf16_t* pv = PL + (size_t)row * CDIN + 1536 + c;
;             const unsigned cur = *(const unsigned*)pv, prv = t > 0 ? *(const unsigned*)(pv - CDIN) : 0u, nxt = t + 1 < SEQ ? *(const unsigned*)(pv + CDIN) : 0u;
;             vr[u][0] = (unsigned short)(cur & 0xffff); vr[u][1] = (unsigned short)(cur >> 16); vr[u][2] = (unsigned short)(prv & 0xffff); vr[u][3] = (unsigned short)(prv >> 16);
;             vr[u][4] = (unsigned short)(nxt & 0xffff); vr[u][5] = (unsigned short)(nxt >> 16);
;         }
; #pragma unroll
;         for (int u = 0; u < 4; ++u) {
;             const int task = task0 + u * stride; const bool ok = task < NLAT * 12;
;             const int row = ok ? task / 12 : 0, h = ok ? task - row * 12 : 0, c = 64 * h + 2 * i;
;             const float y0 = lo16(ya[u]) + lo16(yb[u]), y1 = hi16(ya[u]) + hi16(yb[u]);
;             float sm = y0 + y1;
; #pragma unroll
;             for (int o = 16; o > 0; o >>= 1) sm += __shfl_xor(sm, o);
;             const float mean = sm * (1.0f / 64.0f); const float d0 = y0 - mean, d1 = y1 - mean;
;             float vs = d0 * d0 + d1 * d1;
; #pragma unroll
;             for (int o = 16; o > 0; o >>= 1) vs += __shfl_xor(vs, o);
;             const float rs = rsqrtf(vs * (1.0f / 64.0f) + LNX_EPS);
;             const float x0 = bf2f(vr[u][0]), x1 = bf2f(vr[u][1]);
;             const float v0 = x0 + (0.5f * (bf2f(vr[u][2]) + bf2f(vr[u][4])) - x0) * P.cd_mu[1536 + c], v1 = x1 + (0.5f * (bf2f(vr[u][3]) + bf2f(vr[u][5])) - x1) * P.cd_mu[1536 + c + 1];
;             const float z0 = d0 * rs * P.cd_lnx_w[c] + P.cd_lnx_b[c] + bon[u] * v0, z1 = d1 * rs * P.cd_lnx_w[c + 1] + P.cd_lnx_b[c + 1] + bon[u] * v1;
;             const unsigned gg = *(const unsigned*)(Gt + (size_t)row * 768 + c);
;             if (ok) *(unsigned*)(Y + (size_t)row * DM + c) = pk2(z0 * lo16(gg), z1 * hi16(gg));
	s_sub_u32 s14, s4, 1
	s_add_u32 s6, s3, 2
	s_min_u32 s15, s6, s14
	s_mul_i32 s6, s15, 0x600
	s_add_u32 s72, s60, s6
	s_addc_u32 s73, s61, 0
	global_load_dwordx2 v[40:41], v36, s[72:73]
	global_load_dwordx2 v[54:55], v36, s[72:73] offset:512
	global_load_dwordx2 v[68:69], v36, s[72:73] offset:1024
	s_add_u32 s72, s62, s6
	s_addc_u32 s73, s63, 0
	global_load_dwordx2 v[42:43], v36, s[72:73]
	global_load_dwordx2 v[56:57], v36, s[72:73] offset:512
	global_load_dwordx2 v[70:71], v36, s[72:73] offset:1024
	s_add_u32 s72, s64, s6
	s_addc_u32 s73, s65, 0
	global_load_dwordx2 v[44:45], v36, s[72:73]
	global_load_dwordx2 v[58:59], v36, s[72:73] offset:512
	global_load_dwordx2 v[72:73], v36, s[72:73] offset:1024
	s_mul_i32 s6, s15, 0x1700
	s_add_u32 s72, s66, s6
	s_addc_u32 s73, s67, 0
	global_load_dwordx2 v[46:47], v36, s[72:73]
	global_load_dwordx2 v[60:61], v36, s[72:73] offset:512
	global_load_dwordx2 v[74:75], v36, s[72:73] offset:1024
	s_and_b32 s14, s15, 0x1fff
	s_cmp_lg_u32 s14, 0
	s_cselect_b32 s14, 0x1700, 0
	s_sub_u32 s74, s72, s14
	s_subb_u32 s75, s73, 0
	global_load_dwordx2 v[48:49], v36, s[74:75]
	global_load_dwordx2 v[62:63], v36, s[74:75] offset:512
	global_load_dwordx2 v[76:77], v36, s[74:75] offset:1024
	s_and_b32 s14, s15, 0x1fff
	s_cmp_lg_u32 s14, 0x1fff
	s_cselect_b32 s14, 0x1700, 0
	s_add_u32 s74, s72, s14
	s_addc_u32 s75, s73, 0
	global_load_dwordx2 v[50:51], v36, s[74:75]
	global_load_dwordx2 v[64:65], v36, s[74:75] offset:512
	global_load_dwordx2 v[78:79], v36, s[74:75] offset:1024
	s_mul_i32 s6, s15, 48
	s_add_u32 s72, s68, s6
	s_addc_u32 s73, s69, 0
	global_load_dword v52, v37, s[72:73]
	global_load_dword v66, v37, s[72:73] offset:16
	global_load_dword v80, v37, s[72:73] offset:32
	s_add_u32 s72, s70, s6
	s_addc_u32 s73, s71, 0
	global_load_dword v53, v37, s[72:73]
	global_load_dword v67, v37, s[72:73] offset:16
	global_load_dword v81, v37, s[72:73] offset:32
	s_and_b32 s14, s3, 0x1fff
	s_cmp_lg_u32 s14, 0
	s_cselect_b32 s12, -1, 0
	s_cmp_lg_u32 s14, 0x1fff
	s_cselect_b32 s13, -1, 0
	s_lshl_b32 s6, s3, 11
	s_add_u32 s72, s24, s6
	s_addc_u32 s73, s25, 0
	v_lshlrev_b32_e32 v180, 16, v84
	v_lshlrev_b32_e32 v181, 16, v86
	v_add_f32_e32 v176, v180, v181
	v_and_b32_e32 v180, 0xffff0000, v84
	v_and_b32_e32 v181, 0xffff0000, v86
	v_add_f32_e32 v177, v180, v181
	v_lshlrev_b32_e32 v180, 16, v85
	v_lshlrev_b32_e32 v181, 16, v87
	v_add_f32_e32 v178, v180, v181
	v_and_b32_e32 v180, 0xffff0000, v85
	v_and_b32_e32 v181, 0xffff0000, v87
	v_add_f32_e32 v179, v180, v181
	v_add_f32_e32 v182, v176, v177
	v_add_f32_e32 v182, v182, v178
	v_add_f32_e32 v182, v182, v179
	s_nop 1
	v_add_f32_dpp v182, v182, v182 quad_perm:[1,0,3,2] row_mask:0xf bank_mask:0xf
	s_nop 1
	v_add_f32_dpp v182, v182, v182 quad_perm:[2,3,0,1] row_mask:0xf bank_mask:0xf
	s_nop 1
	v_add_f32_dpp v182, v182, v182 row_half_mirror row_mask:0xf bank_mask:0xf
	s_nop 1
	v_add_f32_dpp v182, v182, v182 row_mirror row_mask:0xf bank_mask:0xf
	s_nop 0
	v_mul_f32_e32 v183, 0x3c800000, v182
	v_sub_f32_e32 v176, v176, v183
	v_sub_f32_e32 v177, v177, v183
	v_sub_f32_e32 v178, v178, v183
	v_sub_f32_e32 v179, v179, v183
	v_mul_f32_e32 v182, v176, v176
	v_fmac_f32_e32 v182, v177, v177
	v_fmac_f32_e32 v182, v178, v178
	v_fmac_f32_e32 v182, v179, v179
	s_nop 1
	v_add_f32_dpp v182, v182, v182 quad_perm:[1,0,3,2] row_mask:0xf bank_mask:0xf
	s_nop 1
	v_add_f32_dpp v182, v182, v182 quad_perm:[2,3,0,1] row_mask:0xf bank_mask:0xf
	s_nop 1
	v_add_f32_dpp v182, v182, v182 row_half_mirror row_mask:0xf bank_mask:0xf
	s_nop 1
	v_add_f32_dpp v182, v182, v182 row_mirror row_mask:0xf bank_mask:0xf
	s_nop 0
	v_fmamk_f32 v184, v182, 0x3c800000, v39
	v_rsq_f32_e32 v184, v184
	v_and_b32_e32 v92, s12, v92
	v_and_b32_e32 v94, s13, v94
	v_lshlrev_b32_e32 v180, 16, v90
	v_lshlrev_b32_e32 v190, 16, v92
	v_lshlrev_b32_e32 v191, 16, v94
	v_add_f32_e32 v190, v190, v191
	v_fma_f32 v190, 0.5, v190, -v180
	v_fma_f32 v186, v190, v0, v180
	v_and_b32_e32 v180, 0xffff0000, v90
	v_and_b32_e32 v190, 0xffff0000, v92
	v_and_b32_e32 v191, 0xffff0000, v94
	v_add_f32_e32 v190, v190, v191
	v_fma_f32 v190, 0.5, v190, -v180
	v_fma_f32 v187, v190, v1, v180
	v_and_b32_e32 v93, s12, v93
	v_and_b32_e32 v95, s13, v95
	v_lshlrev_b32_e32 v180, 16, v91
	v_lshlrev_b32_e32 v190, 16, v93
	v_lshlrev_b32_e32 v191, 16, v95
	v_add_f32_e32 v190, v190, v191
	v_fma_f32 v190, 0.5, v190, -v180
	v_fma_f32 v188, v190, v2, v180
	v_and_b32_e32 v180, 0xffff0000, v91
	v_and_b32_e32 v190, 0xffff0000, v93
	v_and_b32_e32 v191, 0xffff0000, v95
	v_add_f32_e32 v190, v190, v191
	v_fma_f32 v190, 0.5, v190, -v180
	v_fma_f32 v189, v190, v3, v180
	v_add_f32_e32 v185, v96, v97
	v_mul_f32_e32 v176, v176, v184
	v_fma_f32 v176, v176, v4, v8
	v_fmac_f32_e32 v176, v185, v186
	v_mul_f32_e32 v177, v177, v184
	v_fma_f32 v177, v177, v5, v9
	v_fmac_f32_e32 v177, v185, v187
	v_mul_f32_e32 v178, v178, v184
	v_fma_f32 v178, v178, v6, v10
	v_fmac_f32_e32 v178, v185, v188
	v_mul_f32_e32 v179, v179, v184
	v_fma_f32 v179, v179, v7, v11
	v_fmac_f32_e32 v179, v185, v189
	v_lshlrev_b32_e32 v180, 16, v88
	v_mul_f32_e32 v176, v176, v180
	v_and_b32_e32 v180, 0xffff0000, v88
	v_mul_f32_e32 v177, v177, v180
	v_lshlrev_b32_e32 v180, 16, v89
	v_mul_f32_e32 v178, v178, v180
	v_and_b32_e32 v180, 0xffff0000, v89
	v_mul_f32_e32 v179, v179, v180
	v_cvt_pk_bf16_f32 v192, v176, v177
	v_cvt_pk_bf16_f32 v193, v178, v179
	global_store_dwordx2 v36, v[192:193], s[72:73]
	v_lshlrev_b32_e32 v180, 16, v98
	v_lshlrev_b32_e32 v181, 16, v100
	v_add_f32_e32 v176, v180, v181
	v_and_b32_e32 v180, 0xffff0000, v98
	v_and_b32_e32 v181, 0xffff0000, v100
	v_add_f32_e32 v177, v180, v181
	v_lshlrev_b32_e32 v180, 16, v99
; DI float bf2f(bf16_t b) { return __uint_as_float(((unsigned)b) << 16); }
; DI unsigned pk2(float lo, float hi) { const f32x2 v = {lo, hi}; return __builtin_bit_cast(unsigned, __builtin_convertvector(v, bf16x2v)); }
; DI float lo16(unsigned u) { return __uint_as_float(u << 16); }
; DI float hi16(unsigned u) { return __uint_as_float(u & 0xffff0000u); }
; DI void zpass_phase(const Params& P) {
;     ...
;         for (int u = 0; u < 4; ++u) {
;             const int task = task0 + u * stride; const bool ok = task < NLAT * 12;
;             const int row = ok ? task / 12 : 0, h = ok ? task - row * 12 : 0, c = 64 * h + 2 * i;
;             const float y0 = lo16(ya[u]) + lo16(yb[u]), y1 = hi16(ya[u]) + hi16(yb[u]);
;             float sm = y0 + y1;
; #pragma unroll
;             for (int o = 16; o > 0; o >>= 1) sm += __shfl_xor(sm, o);
;             const float mean = sm * (1.0f / 64.0f); const float d0 = y0 - mean, d1 = y1 - mean;
;             float vs = d0 * d0 + d1 * d1;
; #pragma unroll
;             for (int o = 16; o > 0; o >>= 1) vs += __shfl_xor(vs, o);
;             const float rs = rsqrtf(vs * (1.0f / 64.0f) + LNX_EPS);
;             const float x0 = bf2f(vr[u][0]), x1 = bf2f(vr[u][1]);
;             const float v0 = x0 + (0.5f * (bf2f(vr[u][2]) + bf2f(vr[u][4])) - x0) * P.cd_mu[1536 + c], v1 = x1 + (0.5f * (bf2f(vr[u][3]) + bf2f(vr[u][5])) - x1) * P.cd_mu[1536 + c + 1];
;             const float z0 = d0 * rs * P.cd_lnx_w[c] + P.cd_lnx_b[c] + bon[u] * v0, z1 = d1 * rs * P.cd_lnx_w[c + 1] + P.cd_lnx_b[c + 1] + bon[u] * v1;
;             const unsigned gg = *(const unsigned*)(Gt + (size_t)row * 768 + c);
;             if (ok) *(unsigned*)(Y + (size_t)row * DM + c) = pk2(z0 * lo16(gg), z1 * hi16(gg));
	v_lshlrev_b32_e32 v181, 16, v101
	v_add_f32_e32 v178, v180, v181
	v_and_b32_e32 v180, 0xffff0000, v99
	v_and_b32_e32 v181, 0xffff0000, v101
	v_add_f32_e32 v179, v180, v181
	v_add_f32_e32 v182, v176, v177
	v_add_f32_e32 v182, v182, v178
	v_add_f32_e32 v182, v182, v179
	s_nop 1
	v_add_f32_dpp v182, v182, v182 quad_perm:[1,0,3,2] row_mask:0xf bank_mask:0xf
	s_nop 1
	v_add_f32_dpp v182, v182, v182 quad_perm:[2,3,0,1] row_mask:0xf bank_mask:0xf
	s_nop 1
	v_add_f32_dpp v182, v182, v182 row_half_mirror row_mask:0xf bank_mask:0xf
	s_nop 1
	v_add_f32_dpp v182, v182, v182 row_mirror row_mask:0xf bank_mask:0xf
	s_nop 0
	v_mul_f32_e32 v183, 0x3c800000, v182
	v_sub_f32_e32 v176, v176, v183
	v_sub_f32_e32 v177, v177, v183
	v_sub_f32_e32 v178, v178, v183
	v_sub_f32_e32 v179, v179, v183
	v_mul_f32_e32 v182, v176, v176
	v_fmac_f32_e32 v182, v177, v177
	v_fmac_f32_e32 v182, v178, v178
	v_fmac_f32_e32 v182, v179, v179
	s_nop 1
	v_add_f32_dpp v182, v182, v182 quad_perm:[1,0,3,2] row_mask:0xf bank_mask:0xf
	s_nop 1
	v_add_f32_dpp v182, v182, v182 quad_perm:[2,3,0,1] row_mask:0xf bank_mask:0xf
	s_nop 1
	v_add_f32_dpp v182, v182, v182 row_half_mirror row_mask:0xf bank_mask:0xf
	s_nop 1
	v_add_f32_dpp v182, v182, v182 row_mirror row_mask:0xf bank_mask:0xf
	s_nop 0
	v_fmamk_f32 v184, v182, 0x3c800000, v39
	v_rsq_f32_e32 v184, v184
	v_and_b32_e32 v106, s12, v106
	v_and_b32_e32 v108, s13, v108
	v_lshlrev_b32_e32 v180, 16, v104
	v_lshlrev_b32_e32 v190, 16, v106
	v_lshlrev_b32_e32 v191, 16, v108
	v_add_f32_e32 v190, v190, v191
	v_fma_f32 v190, 0.5, v190, -v180
	v_fma_f32 v186, v190, v12, v180
	v_and_b32_e32 v180, 0xffff0000, v104
	v_and_b32_e32 v190, 0xffff0000, v106
	v_and_b32_e32 v191, 0xffff0000, v108
	v_add_f32_e32 v190, v190, v191
	v_fma_f32 v190, 0.5, v190, -v180
	v_fma_f32 v187, v190, v13, v180
	v_and_b32_e32 v107, s12, v107
	v_and_b32_e32 v109, s13, v109
	v_lshlrev_b32_e32 v180, 16, v105
	v_lshlrev_b32_e32 v190, 16, v107
	v_lshlrev_b32_e32 v191, 16, v109
	v_add_f32_e32 v190, v190, v191
	v_fma_f32 v190, 0.5, v190, -v180
	v_fma_f32 v188, v190, v14, v180
	v_and_b32_e32 v180, 0xffff0000, v105
	v_and_b32_e32 v190, 0xffff0000, v107
	v_and_b32_e32 v191, 0xffff0000, v109
	v_add_f32_e32 v190, v190, v191
	v_fma_f32 v190, 0.5, v190, -v180
	v_fma_f32 v189, v190, v15, v180
	v_add_f32_e32 v185, v110, v111
	v_mul_f32_e32 v176, v176, v184
	v_fma_f32 v176, v176, v16, v20
	v_fmac_f32_e32 v176, v185, v186
	v_mul_f32_e32 v177, v177, v184
	v_fma_f32 v177, v177, v17, v21
	v_fmac_f32_e32 v177, v185, v187
	v_mul_f32_e32 v178, v178, v184
	v_fma_f32 v178, v178, v18, v22
	v_fmac_f32_e32 v178, v185, v188
	v_mul_f32_e32 v179, v179, v184
	v_fma_f32 v179, v179, v19, v23
	v_fmac_f32_e32 v179, v185, v189
	v_lshlrev_b32_e32 v180, 16, v102
	v_mul_f32_e32 v176, v176, v180
	v_and_b32_e32 v180, 0xffff0000, v102
	v_mul_f32_e32 v177, v177, v180
	v_lshlrev_b32_e32 v180, 16, v103
	v_mul_f32_e32 v178, v178, v180
	v_and_b32_e32 v180, 0xffff0000, v103
	v_mul_f32_e32 v179, v179, v180
	v_cvt_pk_bf16_f32 v194, v176, v177
	v_cvt_pk_bf16_f32 v195, v178, v179
	global_store_dwordx2 v36, v[194:195], s[72:73] offset:512
	v_lshlrev_b32_e32 v180, 16, v112
	v_lshlrev_b32_e32 v181, 16, v114
	v_add_f32_e32 v176, v180, v181
	v_and_b32_e32 v180, 0xffff0000, v112
	v_and_b32_e32 v181, 0xffff0000, v114
	v_add_f32_e32 v177, v180, v181
	v_lshlrev_b32_e32 v180, 16, v113
	v_lshlrev_b32_e32 v181, 16, v115
	v_add_f32_e32 v178, v180, v181
	v_and_b32_e32 v180, 0xffff0000, v113
	v_and_b32_e32 v181, 0xffff0000, v115
	v_add_f32_e32 v179, v180, v181
	v_add_f32_e32 v182, v176, v177
	v_add_f32_e32 v182, v182, v178
	v_add_f32_e32 v182, v182, v179
	s_nop 1
	v_add_f32_dpp v182, v182, v182 quad_perm:[1,0,3,2] row_mask:0xf bank_mask:0xf
	s_nop 1
	v_add_f32_dpp v182, v182, v182 quad_perm:[2,3,0,1] row_mask:0xf bank_mask:0xf
	s_nop 1
	v_add_f32_dpp v182, v182, v182 row_half_mirror row_mask:0xf bank_mask:0xf
	s_nop 1
	v_add_f32_dpp v182, v182, v182 row_mirror row_mask:0xf bank_mask:0xf
	s_nop 0
	v_mul_f32_e32 v183, 0x3c800000, v182
	v_sub_f32_e32 v176, v176, v183
	v_sub_f32_e32 v177, v177, v183
	v_sub_f32_e32 v178, v178, v183
	v_sub_f32_e32 v179, v179, v183
	v_mul_f32_e32 v182, v176, v176
	v_fmac_f32_e32 v182, v177, v177
	v_fmac_f32_e32 v182, v178, v178
	v_fmac_f32_e32 v182, v179, v179
	s_nop 1
	v_add_f32_dpp v182, v182, v182 quad_perm:[1,0,3,2] row_mask:0xf bank_mask:0xf
	s_nop 1
	v_add_f32_dpp v182, v182, v182 quad_perm:[2,3,0,1] row_mask:0xf bank_mask:0xf
	s_nop 1
	v_add_f32_dpp v182, v182, v182 row_half_mirror row_mask:0xf bank_mask:0xf
	s_nop 1
	v_add_f32_dpp v182, v182, v182 row_mirror row_mask:0xf bank_mask:0xf
	s_nop 0
	v_fmamk_f32 v184, v182, 0x3c800000, v39
	v_rsq_f32_e32 v184, v184
	v_and_b32_e32 v120, s12, v120
	v_and_b32_e32 v122, s13, v122
	v_lshlrev_b32_e32 v180, 16, v118
	v_lshlrev_b32_e32 v190, 16, v120
	v_lshlrev_b32_e32 v191, 16, v122
	v_add_f32_e32 v190, v190, v191
	v_fma_f32 v190, 0.5, v190, -v180
	v_fma_f32 v186, v190, v24, v180
	v_and_b32_e32 v180, 0xffff0000, v118
	v_and_b32_e32 v190, 0xffff0000, v120
	v_and_b32_e32 v191, 0xffff0000, v122
	v_add_f32_e32 v190, v190, v191
	v_fma_f32 v190, 0.5, v190, -v180
	v_fma_f32 v187, v190, v25, v180
	v_and_b32_e32 v121, s12, v121
	v_and_b32_e32 v123, s13, v123
	v_lshlrev_b32_e32 v180, 16, v119
	v_lshlrev_b32_e32 v190, 16, v121
	v_lshlrev_b32_e32 v191, 16, v123
	v_add_f32_e32 v190, v190, v191
	v_fma_f32 v190, 0.5, v190, -v180
	v_fma_f32 v188, v190, v26, v180
	v_and_b32_e32 v180, 0xffff0000, v119
	v_and_b32_e32 v190, 0xffff0000, v121
	v_and_b32_e32 v191, 0xffff0000, v123
	v_add_f32_e32 v190, v190, v191
	v_fma_f32 v190, 0.5, v190, -v180
	v_fma_f32 v189, v190, v27, v180
	v_add_f32_e32 v185, v124, v125
	v_mul_f32_e32 v176, v176, v184
	v_fma_f32 v176, v176, v28, v32
	v_fmac_f32_e32 v176, v185, v186
	v_mul_f32_e32 v177, v177, v184
	v_fma_f32 v177, v177, v29, v33
	v_fmac_f32_e32 v177, v185, v187
	v_mul_f32_e32 v178, v178, v184
	v_fma_f32 v178, v178, v30, v34
	v_fmac_f32_e32 v178, v185, v188
	v_mul_f32_e32 v179, v179, v184
	v_fma_f32 v179, v179, v31, v35
	v_fmac_f32_e32 v179, v185, v189
	v_lshlrev_b32_e32 v180, 16, v116
	v_mul_f32_e32 v176, v176, v180
	v_and_b32_e32 v180, 0xffff0000, v116
	v_mul_f32_e32 v177, v177, v180
	v_lshlrev_b32_e32 v180, 16, v117
	v_mul_f32_e32 v178, v178, v180
	v_and_b32_e32 v180, 0xffff0000, v117
	v_mul_f32_e32 v179, v179, v180
	v_cvt_pk_bf16_f32 v196, v176, v177
	v_cvt_pk_bf16_f32 v197, v178, v179
	global_store_dwordx2 v36, v[196:197], s[72:73] offset:1024
	s_add_u32 s3, s3, 1
	s_waitcnt vmcnt(24)
; DI void zpass_phase(const Params& P) {
;     ...
;         for (int u = 0; u < 4; ++u) {
;             const int task = task0 + u * stride; const bool ok = task < NLAT * 12;
;             const int row = ok ? task / 12 : 0, h = ok ? task - row * 12 : 0, t = row & 8191, c = 64 * h + 2 * i;
;             ya[u] = *(const unsigned*)(YF + (size_t)row * 768 + c); yb[u] = *(const unsigned*)(YB + (size_t)row * 768 + c);
;             bon[u] = BON[(size_t)row * 12 + h] + BON[(size_t)NLAT * 12 + (size_t)row * 12 + h];
;             const bf16_t* pv = PL + (size_t)row * CDIN + 1536 + c;
;             const unsigned cur = *(const unsigned*)pv, prv = t > 0 ? *(const unsigned*)(pv - CDIN) : 0u, nxt = t + 1 < SEQ ? *(const unsigned*)(pv + CDIN) : 0u;
;             vr[u][0] = (unsigned short)(cur & 0xffff); vr[u][1] = (unsigned short)(cur >> 16); vr[u][2] = (unsigned short)(prv & 0xffff); vr[u][3] = (unsigned short)(prv >> 16);
;             vr[u][4] = (unsigned short)(nxt & 0xffff); vr[u][5] = (unsigned short)(nxt >> 16);
;         }
; #pragma unroll
;         for (int u = 0; u < 4; ++u) {
;             const int task = task0 + u * stride; const bool ok = task < NLAT * 12;
;             const int row = ok ? task / 12 : 0, h = ok ? task - row * 12 : 0, c = 64 * h + 2 * i;
;             const float y0 = lo16(ya[u]) + lo16(yb[u]), y1 = hi16(ya[u]) + hi16(yb[u]);
;             float sm = y0 + y1;
; #pragma unroll
;             for (int o = 16; o > 0; o >>= 1) sm += __shfl_xor(sm, o);
;             const float mean = sm * (1.0f / 64.0f); const float d0 = y0 - mean, d1 = y1 - mean;
;             float vs = d0 * d0 + d1 * d1;
; #pragma unroll
;             for (int o = 16; o > 0; o >>= 1) vs += __shfl_xor(vs, o);
;             const float rs = rsqrtf(vs * (1.0f / 64.0f) + LNX_EPS);
;             const float x0 = bf2f(vr[u][0]), x1 = bf2f(vr[u][1]);
;             const float v0 = x0 + (0.5f * (bf2f(vr[u][2]) + bf2f(vr[u][4])) - x0) * P.cd_mu[1536 + c], v1 = x1 + (0.5f * (bf2f(vr[u][3]) + bf2f(vr[u][5])) - x1) * P.cd_mu[1536 + c + 1];
;             const float z0 = d0 * rs * P.cd_lnx_w[c] + P.cd_lnx_b[c] + bon[u] * v0, z1 = d1 * rs * P.cd_lnx_w[c + 1] + P.cd_lnx_b[c + 1] + bon[u] * v1;
;             const unsigned gg = *(const unsigned*)(Gt + (size_t)row * 768 + c);
;             if (ok) *(unsigned*)(Y + (size_t)row * DM + c) = pk2(z0 * lo16(gg), z1 * hi16(gg));
	s_sub_u32 s14, s4, 1
	s_add_u32 s6, s3, 2
	s_min_u32 s15, s6, s14
	s_mul_i32 s6, s15, 0x600
	s_add_u32 s72, s60, s6
	s_addc_u32 s73, s61, 0
	global_load_dwordx2 v[84:85], v36, s[72:73]
	global_load_dwordx2 v[98:99], v36, s[72:73] offset:512
	global_load_dwordx2 v[112:113], v36, s[72:73] offset:1024
	s_add_u32 s72, s62, s6
	s_addc_u32 s73, s63, 0
	global_load_dwordx2 v[86:87], v36, s[72:73]
	global_load_dwordx2 v[100:101], v36, s[72:73] offset:512
	global_load_dwordx2 v[114:115], v36, s[72:73] offset:1024
	s_add_u32 s72, s64, s6
	s_addc_u32 s73, s65, 0
	global_load_dwordx2 v[88:89], v36, s[72:73]
	global_load_dwordx2 v[102:103], v36, s[72:73] offset:512
	global_load_dwordx2 v[116:117], v36, s[72:73] offset:1024
	s_mul_i32 s6, s15, 0x1700
	s_add_u32 s72, s66, s6
	s_addc_u32 s73, s67, 0
	global_load_dwordx2 v[90:91], v36, s[72:73]
	global_load_dwordx2 v[104:105], v36, s[72:73] offset:512
	global_load_dwordx2 v[118:119], v36, s[72:73] offset:1024
	s_and_b32 s14, s15, 0x1fff
	s_cmp_lg_u32 s14, 0
	s_cselect_b32 s14, 0x1700, 0
	s_sub_u32 s74, s72, s14
	s_subb_u32 s75, s73, 0
	global_load_dwordx2 v[92:93], v36, s[74:75]
	global_load_dwordx2 v[106:107], v36, s[74:75] offset:512
	global_load_dwordx2 v[120:121], v36, s[74:75] offset:1024
	s_and_b32 s14, s15, 0x1fff
	s_cmp_lg_u32 s14, 0x1fff
	s_cselect_b32 s14, 0x1700, 0
	s_add_u32 s74, s72, s14
	s_addc_u32 s75, s73, 0
	global_load_dwordx2 v[94:95], v36, s[74:75]
	global_load_dwordx2 v[108:109], v36, s[74:75] offset:512
	global_load_dwordx2 v[122:123], v36, s[74:75] offset:1024
	s_mul_i32 s6, s15, 48
	s_add_u32 s72, s68, s6
	s_addc_u32 s73, s69, 0
	global_load_dword v96, v37, s[72:73]
	global_load_dword v110, v37, s[72:73] offset:16
	global_load_dword v124, v37, s[72:73] offset:32
	s_add_u32 s72, s70, s6
	s_addc_u32 s73, s71, 0
	global_load_dword v97, v37, s[72:73]
	global_load_dword v111, v37, s[72:73] offset:16
	global_load_dword v125, v37, s[72:73] offset:32
	s_and_b32 s14, s3, 0x1fff
	s_cmp_lg_u32 s14, 0
	s_cselect_b32 s12, -1, 0
	s_cmp_lg_u32 s14, 0x1fff
	s_cselect_b32 s13, -1, 0
	s_lshl_b32 s6, s3, 11
	s_add_u32 s72, s24, s6
	s_addc_u32 s73, s25, 0
	v_lshlrev_b32_e32 v180, 16, v128
	v_lshlrev_b32_e32 v181, 16, v130
	v_add_f32_e32 v176, v180, v181
	v_and_b32_e32 v180, 0xffff0000, v128
	v_and_b32_e32 v181, 0xffff0000, v130
	v_add_f32_e32 v177, v180, v181
	v_lshlrev_b32_e32 v180, 16, v129
	v_lshlrev_b32_e32 v181, 16, v131
	v_add_f32_e32 v178, v180, v181
	v_and_b32_e32 v180, 0xffff0000, v129
	v_and_b32_e32 v181, 0xffff0000, v131
	v_add_f32_e32 v179, v180, v181
	v_add_f32_e32 v182, v176, v177
	v_add_f32_e32 v182, v182, v178
	v_add_f32_e32 v182, v182, v179
	s_nop 1
	v_add_f32_dpp v182, v182, v182 quad_perm:[1,0,3,2] row_mask:0xf bank_mask:0xf
	s_nop 1
	v_add_f32_dpp v182, v182, v182 quad_perm:[2,3,0,1] row_mask:0xf bank_mask:0xf
	s_nop 1
	v_add_f32_dpp v182, v182, v182 row_half_mirror row_mask:0xf bank_mask:0xf
	s_nop 1
	v_add_f32_dpp v182, v182, v182 row_mirror row_mask:0xf bank_mask:0xf
	s_nop 0
	v_mul_f32_e32 v183, 0x3c800000, v182
	v_sub_f32_e32 v176, v176, v183
	v_sub_f32_e32 v177, v177, v183
	v_sub_f32_e32 v178, v178, v183
	v_sub_f32_e32 v179, v179, v183
	v_mul_f32_e32 v182, v176, v176
	v_fmac_f32_e32 v182, v177, v177
	v_fmac_f32_e32 v182, v178, v178
	v_fmac_f32_e32 v182, v179, v179
	s_nop 1
	v_add_f32_dpp v182, v182, v182 quad_perm:[1,0,3,2] row_mask:0xf bank_mask:0xf
	s_nop 1
	v_add_f32_dpp v182, v182, v182 quad_perm:[2,3,0,1] row_mask:0xf bank_mask:0xf
	s_nop 1
	v_add_f32_dpp v182, v182, v182 row_half_mirror row_mask:0xf bank_mask:0xf
	s_nop 1
	v_add_f32_dpp v182, v182, v182 row_mirror row_mask:0xf bank_mask:0xf
	s_nop 0
	v_fmamk_f32 v184, v182, 0x3c800000, v39
	v_rsq_f32_e32 v184, v184
	v_and_b32_e32 v136, s12, v136
	v_and_b32_e32 v138, s13, v138
	v_lshlrev_b32_e32 v180, 16, v134
	v_lshlrev_b32_e32 v190, 16, v136
	v_lshlrev_b32_e32 v191, 16, v138
	v_add_f32_e32 v190, v190, v191
	v_fma_f32 v190, 0.5, v190, -v180
	v_fma_f32 v186, v190, v0, v180
	v_and_b32_e32 v180, 0xffff0000, v134
	v_and_b32_e32 v190, 0xffff0000, v136
	v_and_b32_e32 v191, 0xffff0000, v138
	v_add_f32_e32 v190, v190, v191
	v_fma_f32 v190, 0.5, v190, -v180
	v_fma_f32 v187, v190, v1, v180
	v_and_b32_e32 v137, s12, v137
	v_and_b32_e32 v139, s13, v139
	v_lshlrev_b32_e32 v180, 16, v135
	v_lshlrev_b32_e32 v190, 16, v137
	v_lshlrev_b32_e32 v191, 16, v139
	v_add_f32_e32 v190, v190, v191
	v_fma_f32 v190, 0.5, v190, -v180
	v_fma_f32 v188, v190, v2, v180
	v_and_b32_e32 v180, 0xffff0000, v135
	v_and_b32_e32 v190, 0xffff0000, v137
	v_and_b32_e32 v191, 0xffff0000, v139
	v_add_f32_e32 v190, v190, v191
	v_fma_f32 v190, 0.5, v190, -v180
	v_fma_f32 v189, v190, v3, v180
	v_add_f32_e32 v185, v140, v141
	v_mul_f32_e32 v176, v176, v184
	v_fma_f32 v176, v176, v4, v8
	v_fmac_f32_e32 v176, v185, v186
	v_mul_f32_e32 v177, v177, v184
	v_fma_f32 v177, v177, v5, v9
	v_fmac_f32_e32 v177, v185, v187
	v_mul_f32_e32 v178, v178, v184
	v_fma_f32 v178, v178, v6, v10
	v_fmac_f32_e32 v178, v185, v188
	v_mul_f32_e32 v179, v179, v184
	v_fma_f32 v179, v179, v7, v11
	v_fmac_f32_e32 v179, v185, v189
	v_lshlrev_b32_e32 v180, 16, v132
	v_mul_f32_e32 v176, v176, v180
	v_and_b32_e32 v180, 0xffff0000, v132
	v_mul_f32_e32 v177, v177, v180
	v_lshlrev_b32_e32 v180, 16, v133
	v_mul_f32_e32 v178, v178, v180
	v_and_b32_e32 v180, 0xffff0000, v133
	v_mul_f32_e32 v179, v179, v180
	v_cvt_pk_bf16_f32 v192, v176, v177
	v_cvt_pk_bf16_f32 v193, v178, v179
	global_store_dwordx2 v36, v[192:193], s[72:73]
	v_lshlrev_b32_e32 v180, 16, v142
	v_lshlrev_b32_e32 v181, 16, v144
	v_add_f32_e32 v176, v180, v181
	v_and_b32_e32 v180, 0xffff0000, v142
	v_and_b32_e32 v181, 0xffff0000, v144
; DI float bf2f(bf16_t b) { return __uint_as_float(((unsigned)b) << 16); }
; DI unsigned pk2(float lo, float hi) { const f32x2 v = {lo, hi}; return __builtin_bit_cast(unsigned, __builtin_convertvector(v, bf16x2v)); }
; DI float lo16(unsigned u) { return __uint_as_float(u << 16); }
; DI float hi16(unsigned u) { return __uint_as_float(u & 0xffff0000u); }
; DI void zpass_phase(const Params& P) {
;     ...
;         for (int u = 0; u < 4; ++u) {
;             const int task = task0 + u * stride; const bool ok = task < NLAT * 12;
;             const int row = ok ? task / 12 : 0, h = ok ? task - row * 12 : 0, c = 64 * h + 2 * i;
;             const float y0 = lo16(ya[u]) + lo16(yb[u]), y1 = hi16(ya[u]) + hi16(yb[u]);
;             float sm = y0 + y1;
; #pragma unroll
;             for (int o = 16; o > 0; o >>= 1) sm += __shfl_xor(sm, o);
;             const float mean = sm * (1.0f / 64.0f); const float d0 = y0 - mean, d1 = y1 - mean;
;             float vs = d0 * d0 + d1 * d1;
; #pragma unroll
;             for (int o = 16; o > 0; o >>= 1) vs += __shfl_xor(vs, o);
;             const float rs = rsqrtf(vs * (1.0f / 64.0f) + LNX_EPS);
;             const float x0 = bf2f(vr[u][0]), x1 = bf2f(vr[u][1]);
;             const float v0 = x0 + (0.5f * (bf2f(vr[u][2]) + bf2f(vr[u][4])) - x0) * P.cd_mu[1536 + c], v1 = x1 + (0.5f * (bf2f(vr[u][3]) + bf2f(vr[u][5])) - x1) * P.cd_mu[1536 + c + 1];
;             const float z0 = d0 * rs * P.cd_lnx_w[c] + P.cd_lnx_b[c] + bon[u] * v0, z1 = d1 * rs * P.cd_lnx_w[c + 1] + P.cd_lnx_b[c + 1] + bon[u] * v1;
;             const unsigned gg = *(const unsigned*)(Gt + (size_t)row * 768 + c);
;             if (ok) *(unsigned*)(Y + (size_t)row * DM + c) = pk2(z0 * lo16(gg), z1 * hi16(gg));
	v_add_f32_e32 v177, v180, v181
	v_lshlrev_b32_e32 v180, 16, v143
	v_lshlrev_b32_e32 v181, 16, v145
	v_add_f32_e32 v178, v180, v181
	v_and_b32_e32 v180, 0xffff0000, v143
	v_and_b32_e32 v181, 0xffff0000, v145
	v_add_f32_e32 v179, v180, v181
	v_add_f32_e32 v182, v176, v177
	v_add_f32_e32 v182, v182, v178
	v_add_f32_e32 v182, v182, v179
	s_nop 1
	v_add_f32_dpp v182, v182, v182 quad_perm:[1,0,3,2] row_mask:0xf bank_mask:0xf
	s_nop 1
	v_add_f32_dpp v182, v182, v182 quad_perm:[2,3,0,1] row_mask:0xf bank_mask:0xf
	s_nop 1
	v_add_f32_dpp v182, v182, v182 row_half_mirror row_mask:0xf bank_mask:0xf
	s_nop 1
	v_add_f32_dpp v182, v182, v182 row_mirror row_mask:0xf bank_mask:0xf
	s_nop 0
	v_mul_f32_e32 v183, 0x3c800000, v182
	v_sub_f32_e32 v176, v176, v183
	v_sub_f32_e32 v177, v177, v183
	v_sub_f32_e32 v178, v178, v183
	v_sub_f32_e32 v179, v179, v183
	v_mul_f32_e32 v182, v176, v176
	v_fmac_f32_e32 v182, v177, v177
	v_fmac_f32_e32 v182, v178, v178
	v_fmac_f32_e32 v182, v179, v179
	s_nop 1
	v_add_f32_dpp v182, v182, v182 quad_perm:[1,0,3,2] row_mask:0xf bank_mask:0xf
	s_nop 1
	v_add_f32_dpp v182, v182, v182 quad_perm:[2,3,0,1] row_mask:0xf bank_mask:0xf
	s_nop 1
	v_add_f32_dpp v182, v182, v182 row_half_mirror row_mask:0xf bank_mask:0xf
	s_nop 1
	v_add_f32_dpp v182, v182, v182 row_mirror row_mask:0xf bank_mask:0xf
	s_nop 0
	v_fmamk_f32 v184, v182, 0x3c800000, v39
	v_rsq_f32_e32 v184, v184
	v_and_b32_e32 v150, s12, v150
	v_and_b32_e32 v152, s13, v152
	v_lshlrev_b32_e32 v180, 16, v148
	v_lshlrev_b32_e32 v190, 16, v150
	v_lshlrev_b32_e32 v191, 16, v152
	v_add_f32_e32 v190, v190, v191
	v_fma_f32 v190, 0.5, v190, -v180
	v_fma_f32 v186, v190, v12, v180
	v_and_b32_e32 v180, 0xffff0000, v148
	v_and_b32_e32 v190, 0xffff0000, v150
	v_and_b32_e32 v191, 0xffff0000, v152
	v_add_f32_e32 v190, v190, v191
	v_fma_f32 v190, 0.5, v190, -v180
	v_fma_f32 v187, v190, v13, v180
	v_and_b32_e32 v151, s12, v151
	v_and_b32_e32 v153, s13, v153
	v_lshlrev_b32_e32 v180, 16, v149
	v_lshlrev_b32_e32 v190, 16, v151
	v_lshlrev_b32_e32 v191, 16, v153
	v_add_f32_e32 v190, v190, v191
	v_fma_f32 v190, 0.5, v190, -v180
	v_fma_f32 v188, v190, v14, v180
	v_and_b32_e32 v180, 0xffff0000, v149
	v_and_b32_e32 v190, 0xffff0000, v151
	v_and_b32_e32 v191, 0xffff0000, v153
	v_add_f32_e32 v190, v190, v191
	v_fma_f32 v190, 0.5, v190, -v180
	v_fma_f32 v189, v190, v15, v180
	v_add_f32_e32 v185, v154, v155
	v_mul_f32_e32 v176, v176, v184
	v_fma_f32 v176, v176, v16, v20
	v_fmac_f32_e32 v176, v185, v186
	v_mul_f32_e32 v177, v177, v184
	v_fma_f32 v177, v177, v17, v21
	v_fmac_f32_e32 v177, v185, v187
	v_mul_f32_e32 v178, v178, v184
	v_fma_f32 v178, v178, v18, v22
	v_fmac_f32_e32 v178, v185, v188
	v_mul_f32_e32 v179, v179, v184
	v_fma_f32 v179, v179, v19, v23
	v_fmac_f32_e32 v179, v185, v189
	v_lshlrev_b32_e32 v180, 16, v146
	v_mul_f32_e32 v176, v176, v180
	v_and_b32_e32 v180, 0xffff0000, v146
	v_mul_f32_e32 v177, v177, v180
	v_lshlrev_b32_e32 v180, 16, v147
	v_mul_f32_e32 v178, v178, v180
	v_and_b32_e32 v180, 0xffff0000, v147
	v_mul_f32_e32 v179, v179, v180
	v_cvt_pk_bf16_f32 v194, v176, v177
	v_cvt_pk_bf16_f32 v195, v178, v179
	global_store_dwordx2 v36, v[194:195], s[72:73] offset:512
	v_lshlrev_b32_e32 v180, 16, v156
	v_lshlrev_b32_e32 v181, 16, v158
	v_add_f32_e32 v176, v180, v181
	v_and_b32_e32 v180, 0xffff0000, v156
	v_and_b32_e32 v181, 0xffff0000, v158
	v_add_f32_e32 v177, v180, v181
	v_lshlrev_b32_e32 v180, 16, v157
	v_lshlrev_b32_e32 v181, 16, v159
	v_add_f32_e32 v178, v180, v181
	v_and_b32_e32 v180, 0xffff0000, v157
	v_and_b32_e32 v181, 0xffff0000, v159
	v_add_f32_e32 v179, v180, v181
	v_add_f32_e32 v182, v176, v177
	v_add_f32_e32 v182, v182, v178
	v_add_f32_e32 v182, v182, v179
	s_nop 1
	v_add_f32_dpp v182, v182, v182 quad_perm:[1,0,3,2] row_mask:0xf bank_mask:0xf
	s_nop 1
	v_add_f32_dpp v182, v182, v182 quad_perm:[2,3,0,1] row_mask:0xf bank_mask:0xf
	s_nop 1
	v_add_f32_dpp v182, v182, v182 row_half_mirror row_mask:0xf bank_mask:0xf
	s_nop 1
	v_add_f32_dpp v182, v182, v182 row_mirror row_mask:0xf bank_mask:0xf
	s_nop 0
	v_mul_f32_e32 v183, 0x3c800000, v182
	v_sub_f32_e32 v176, v176, v183
	v_sub_f32_e32 v177, v177, v183
	v_sub_f32_e32 v178, v178, v183
	v_sub_f32_e32 v179, v179, v183
	v_mul_f32_e32 v182, v176, v176
	v_fmac_f32_e32 v182, v177, v177
	v_fmac_f32_e32 v182, v178, v178
	v_fmac_f32_e32 v182, v179, v179
	s_nop 1
	v_add_f32_dpp v182, v182, v182 quad_perm:[1,0,3,2] row_mask:0xf bank_mask:0xf
	s_nop 1
	v_add_f32_dpp v182, v182, v182 quad_perm:[2,3,0,1] row_mask:0xf bank_mask:0xf
	s_nop 1
	v_add_f32_dpp v182, v182, v182 row_half_mirror row_mask:0xf bank_mask:0xf
	s_nop 1
	v_add_f32_dpp v182, v182, v182 row_mirror row_mask:0xf bank_mask:0xf
	s_nop 0
	v_fmamk_f32 v184, v182, 0x3c800000, v39
	v_rsq_f32_e32 v184, v184
	v_and_b32_e32 v164, s12, v164
	v_and_b32_e32 v166, s13, v166
	v_lshlrev_b32_e32 v180, 16, v162
	v_lshlrev_b32_e32 v190, 16, v164
	v_lshlrev_b32_e32 v191, 16, v166
	v_add_f32_e32 v190, v190, v191
	v_fma_f32 v190, 0.5, v190, -v180
	v_fma_f32 v186, v190, v24, v180
	v_and_b32_e32 v180, 0xffff0000, v162
	v_and_b32_e32 v190, 0xffff0000, v164
	v_and_b32_e32 v191, 0xffff0000, v166
	v_add_f32_e32 v190, v190, v191
	v_fma_f32 v190, 0.5, v190, -v180
	v_fma_f32 v187, v190, v25, v180
	v_and_b32_e32 v165, s12, v165
	v_and_b32_e32 v167, s13, v167
	v_lshlrev_b32_e32 v180, 16, v163
	v_lshlrev_b32_e32 v190, 16, v165
	v_lshlrev_b32_e32 v191, 16, v167
	v_add_f32_e32 v190, v190, v191
	v_fma_f32 v190, 0.5, v190, -v180
	v_fma_f32 v188, v190, v26, v180
	v_and_b32_e32 v180, 0xffff0000, v163
	v_and_b32_e32 v190, 0xffff0000, v165
	v_and_b32_e32 v191, 0xffff0000, v167
	v_add_f32_e32 v190, v190, v191
	v_fma_f32 v190, 0.5, v190, -v180
	v_fma_f32 v189, v190, v27, v180
	v_add_f32_e32 v185, v168, v169
	v_mul_f32_e32 v176, v176, v184
	v_fma_f32 v176, v176, v28, v32
	v_fmac_f32_e32 v176, v185, v186
	v_mul_f32_e32 v177, v177, v184
	v_fma_f32 v177, v177, v29, v33
	v_fmac_f32_e32 v177, v185, v187
	v_mul_f32_e32 v178, v178, v184
	v_fma_f32 v178, v178, v30, v34
	v_fmac_f32_e32 v178, v185, v188
	v_mul_f32_e32 v179, v179, v184
	v_fma_f32 v179, v179, v31, v35
	v_fmac_f32_e32 v179, v185, v189
	v_lshlrev_b32_e32 v180, 16, v160
	v_mul_f32_e32 v176, v176, v180
	v_and_b32_e32 v180, 0xffff0000, v160
	v_mul_f32_e32 v177, v177, v180
	v_lshlrev_b32_e32 v180, 16, v161
	v_mul_f32_e32 v178, v178, v180
	v_and_b32_e32 v180, 0xffff0000, v161
	v_mul_f32_e32 v179, v179, v180
	v_cvt_pk_bf16_f32 v196, v176, v177
	v_cvt_pk_bf16_f32 v197, v178, v179
	global_store_dwordx2 v36, v[196:197], s[72:73] offset:1024
	s_add_u32 s3, s3, 1
	s_sub_u32 s5, s5, 1
	s_cmp_lg_u32 s5, 0
	s_cbranch_scc1 .Lzp_loop
; DI void zpass_phase(const Params& P) {
;     ...
;         for (int u = 0; u < 4; ++u) {
;             const int task = task0 + u * stride; const bool ok = task < NLAT * 12;
;             const int row = ok ? task / 12 : 0, h = ok ? task - row * 12 : 0, t = row & 8191, c = 64 * h + 2 * i;
;             ya[u] = *(const unsigned*)(YF + (size_t)row * 768 + c); yb[u] = *(const unsigned*)(YB + (size_t)row * 768 + c);
;             bon[u] = BON[(size_t)row * 12 + h] + BON[(size_t)NLAT * 12 + (size_t)row * 12 + h];
;             const bf16_t* pv = PL + (size_t)row * CDIN + 1536 + c;
;             const unsigned cur = *(const unsigned*)pv, prv = t > 0 ? *(const unsigned*)(pv - CDIN) : 0u, nxt = t + 1 < SEQ ? *(const unsigned*)(pv + CDIN) : 0u;
;             vr[u][0] = (unsigned short)(cur & 0xffff); vr[u][1] = (unsigned short)(cur >> 16); vr[u][2] = (unsigned short)(prv & 0xffff); vr[u][3] = (unsigned short)(prv >> 16);
;             vr[u][4] = (unsigned short)(nxt & 0xffff); vr[u][5] = (unsigned short)(nxt >> 16);
;         }
; #pragma unroll
;         for (int u = 0; u < 4; ++u) {
;             const int task = task0 + u * stride; const bool ok = task < NLAT * 12;
;             const int row = ok ? task / 12 : 0, h = ok ? task - row * 12 : 0, c = 64 * h + 2 * i;
;             const float y0 = lo16(ya[u]) + lo16(yb[u]), y1 = hi16(ya[u]) + hi16(yb[u]);
;             float sm = y0 + y1;
; #pragma unroll
;             for (int o = 16; o > 0; o >>= 1) sm += __shfl_xor(sm, o);
;             const float mean = sm * (1.0f / 64.0f); const float d0 = y0 - mean, d1 = y1 - mean;
;             float vs = d0 * d0 + d1 * d1;
; #pragma unroll
;             for (int o = 16; o > 0; o >>= 1) vs += __shfl_xor(vs, o);
;             const float rs = rsqrtf(vs * (1.0f / 64.0f) + LNX_EPS);
;             const float x0 = bf2f(vr[u][0]), x1 = bf2f(vr[u][1]);
;             const float v0 = x0 + (0.5f * (bf2f(vr[u][2]) + bf2f(vr[u][4])) - x0) * P.cd_mu[1536 + c], v1 = x1 + (0.5f * (bf2f(vr[u][3]) + bf2f(vr[u][5])) - x1) * P.cd_mu[1536 + c + 1];
;             const float z0 = d0 * rs * P.cd_lnx_w[c] + P.cd_lnx_b[c] + bon[u] * v0, z1 = d1 * rs * P.cd_lnx_w[c + 1] + P.cd_lnx_b[c + 1] + bon[u] * v1;
;             const unsigned gg = *(const unsigned*)(Gt + (size_t)row * 768 + c);
;             if (ok) *(unsigned*)(Y + (size_t)row * DM + c) = pk2(z0 * lo16(gg), z1 * hi16(gg));
	s_waitcnt vmcnt(24)
	s_sub_u32 s14, s4, 1
	s_add_u32 s6, s3, 2
	s_min_u32 s15, s6, s14
	s_mul_i32 s6, s15, 0x600
	s_add_u32 s72, s60, s6
	s_addc_u32 s73, s61, 0
	global_load_dwordx2 v[128:129], v36, s[72:73]
	global_load_dwordx2 v[142:143], v36, s[72:73] offset:512
	global_load_dwordx2 v[156:157], v36, s[72:73] offset:1024
	s_add_u32 s72, s62, s6
	s_addc_u32 s73, s63, 0
	global_load_dwordx2 v[130:131], v36, s[72:73]
	global_load_dwordx2 v[144:145], v36, s[72:73] offset:512
	global_load_dwordx2 v[158:159], v36, s[72:73] offset:1024
	s_add_u32 s72, s64, s6
	s_addc_u32 s73, s65, 0
	global_load_dwordx2 v[132:133], v36, s[72:73]
	global_load_dwordx2 v[146:147], v36, s[72:73] offset:512
	global_load_dwordx2 v[160:161], v36, s[72:73] offset:1024
	s_mul_i32 s6, s15, 0x1700
	s_add_u32 s72, s66, s6
	s_addc_u32 s73, s67, 0
	global_load_dwordx2 v[134:135], v36, s[72:73]
	global_load_dwordx2 v[148:149], v36, s[72:73] offset:512
	global_load_dwordx2 v[162:163], v36, s[72:73] offset:1024
	s_and_b32 s14, s15, 0x1fff
	s_cmp_lg_u32 s14, 0
	s_cselect_b32 s14, 0x1700, 0
	s_sub_u32 s74, s72, s14
	s_subb_u32 s75, s73, 0
	global_load_dwordx2 v[136:137], v36, s[74:75]
	global_load_dwordx2 v[150:151], v36, s[74:75] offset:512
	global_load_dwordx2 v[164:165], v36, s[74:75] offset:1024
	s_and_b32 s14, s15, 0x1fff
	s_cmp_lg_u32 s14, 0x1fff
	s_cselect_b32 s14, 0x1700, 0
	s_add_u32 s74, s72, s14
	s_addc_u32 s75, s73, 0
	global_load_dwordx2 v[138:139], v36, s[74:75]
	global_load_dwordx2 v[152:153], v36, s[74:75] offset:512
	global_load_dwordx2 v[166:167], v36, s[74:75] offset:1024
	s_mul_i32 s6, s15, 48
	s_add_u32 s72, s68, s6
	s_addc_u32 s73, s69, 0
	global_load_dword v140, v37, s[72:73]
	global_load_dword v154, v37, s[72:73] offset:16
	global_load_dword v168, v37, s[72:73] offset:32
	s_add_u32 s72, s70, s6
	s_addc_u32 s73, s71, 0
	global_load_dword v141, v37, s[72:73]
	global_load_dword v155, v37, s[72:73] offset:16
	global_load_dword v169, v37, s[72:73] offset:32
	s_and_b32 s14, s3, 0x1fff
	s_cmp_lg_u32 s14, 0
	s_cselect_b32 s12, -1, 0
	s_cmp_lg_u32 s14, 0x1fff
	s_cselect_b32 s13, -1, 0
	s_lshl_b32 s6, s3, 11
	s_add_u32 s72, s24, s6
	s_addc_u32 s73, s25, 0
	v_lshlrev_b32_e32 v180, 16, v40
	v_lshlrev_b32_e32 v181, 16, v42
	v_add_f32_e32 v176, v180, v181
	v_and_b32_e32 v180, 0xffff0000, v40
	v_and_b32_e32 v181, 0xffff0000, v42
	v_add_f32_e32 v177, v180, v181
	v_lshlrev_b32_e32 v180, 16, v41
	v_lshlrev_b32_e32 v181, 16, v43
	v_add_f32_e32 v178, v180, v181
	v_and_b32_e32 v180, 0xffff0000, v41
	v_and_b32_e32 v181, 0xffff0000, v43
	v_add_f32_e32 v179, v180, v181
	v_add_f32_e32 v182, v176, v177
	v_add_f32_e32 v182, v182, v178
	v_add_f32_e32 v182, v182, v179
	s_nop 1
	v_add_f32_dpp v182, v182, v182 quad_perm:[1,0,3,2] row_mask:0xf bank_mask:0xf
	s_nop 1
	v_add_f32_dpp v182, v182, v182 quad_perm:[2,3,0,1] row_mask:0xf bank_mask:0xf
	s_nop 1
	v_add_f32_dpp v182, v182, v182 row_half_mirror row_mask:0xf bank_mask:0xf
	s_nop 1
	v_add_f32_dpp v182, v182, v182 row_mirror row_mask:0xf bank_mask:0xf
	s_nop 0
	v_mul_f32_e32 v183, 0x3c800000, v182
	v_sub_f32_e32 v176, v176, v183
	v_sub_f32_e32 v177, v177, v183
	v_sub_f32_e32 v178, v178, v183
	v_sub_f32_e32 v179, v179, v183
	v_mul_f32_e32 v182, v176, v176
	v_fmac_f32_e32 v182, v177, v177
	v_fmac_f32_e32 v182, v178, v178
	v_fmac_f32_e32 v182, v179, v179
	s_nop 1
	v_add_f32_dpp v182, v182, v182 quad_perm:[1,0,3,2] row_mask:0xf bank_mask:0xf
	s_nop 1
	v_add_f32_dpp v182, v182, v182 quad_perm:[2,3,0,1] row_mask:0xf bank_mask:0xf
	s_nop 1
	v_add_f32_dpp v182, v182, v182 row_half_mirror row_mask:0xf bank_mask:0xf
	s_nop 1
	v_add_f32_dpp v182, v182, v182 row_mirror row_mask:0xf bank_mask:0xf
	s_nop 0
	v_fmamk_f32 v184, v182, 0x3c800000, v39
	v_rsq_f32_e32 v184, v184
	v_and_b32_e32 v48, s12, v48
	v_and_b32_e32 v50, s13, v50
	v_lshlrev_b32_e32 v180, 16, v46
	v_lshlrev_b32_e32 v190, 16, v48
	v_lshlrev_b32_e32 v191, 16, v50
	v_add_f32_e32 v190, v190, v191
	v_fma_f32 v190, 0.5, v190, -v180
	v_fma_f32 v186, v190, v0, v180
	v_and_b32_e32 v180, 0xffff0000, v46
	v_and_b32_e32 v190, 0xffff0000, v48
	v_and_b32_e32 v191, 0xffff0000, v50
	v_add_f32_e32 v190, v190, v191
	v_fma_f32 v190, 0.5, v190, -v180
	v_fma_f32 v187, v190, v1, v180
	v_and_b32_e32 v49, s12, v49
	v_and_b32_e32 v51, s13, v51
	v_lshlrev_b32_e32 v180, 16, v47
	v_lshlrev_b32_e32 v190, 16, v49
	v_lshlrev_b32_e32 v191, 16, v51
	v_add_f32_e32 v190, v190, v191
	v_fma_f32 v190, 0.5, v190, -v180
	v_fma_f32 v188, v190, v2, v180
	v_and_b32_e32 v180, 0xffff0000, v47
	v_and_b32_e32 v190, 0xffff0000, v49
	v_and_b32_e32 v191, 0xffff0000, v51
	v_add_f32_e32 v190, v190, v191
	v_fma_f32 v190, 0.5, v190, -v180
	v_fma_f32 v189, v190, v3, v180
	v_add_f32_e32 v185, v52, v53
	v_mul_f32_e32 v176, v176, v184
	v_fma_f32 v176, v176, v4, v8
	v_fmac_f32_e32 v176, v185, v186
	v_mul_f32_e32 v177, v177, v184
	v_fma_f32 v177, v177, v5, v9
	v_fmac_f32_e32 v177, v185, v187
	v_mul_f32_e32 v178, v178, v184
	v_fma_f32 v178, v178, v6, v10
	v_fmac_f32_e32 v178, v185, v188
	v_mul_f32_e32 v179, v179, v184
	v_fma_f32 v179, v179, v7, v11
	v_fmac_f32_e32 v179, v185, v189
	v_lshlrev_b32_e32 v180, 16, v44
	v_mul_f32_e32 v176, v176, v180
	v_and_b32_e32 v180, 0xffff0000, v44
	v_mul_f32_e32 v177, v177, v180
	v_lshlrev_b32_e32 v180, 16, v45
	v_mul_f32_e32 v178, v178, v180
	v_and_b32_e32 v180, 0xffff0000, v45
	v_mul_f32_e32 v179, v179, v180
	v_cvt_pk_bf16_f32 v192, v176, v177
	v_cvt_pk_bf16_f32 v193, v178, v179
	global_store_dwordx2 v36, v[192:193], s[72:73]
	v_lshlrev_b32_e32 v180, 16, v54
	v_lshlrev_b32_e32 v181, 16, v56
	v_add_f32_e32 v176, v180, v181
	v_and_b32_e32 v180, 0xffff0000, v54
	v_and_b32_e32 v181, 0xffff0000, v56
; DI float bf2f(bf16_t b) { return __uint_as_float(((unsigned)b) << 16); }
; DI unsigned pk2(float lo, float hi) { const f32x2 v = {lo, hi}; return __builtin_bit_cast(unsigned, __builtin_convertvector(v, bf16x2v)); }
; DI float lo16(unsigned u) { return __uint_as_float(u << 16); }
; DI float hi16(unsigned u) { return __uint_as_float(u & 0xffff0000u); }
; DI void zpass_phase(const Params& P) {
;     ...
;         for (int u = 0; u < 4; ++u) {
;             const int task = task0 + u * stride; const bool ok = task < NLAT * 12;
;             const int row = ok ? task / 12 : 0, h = ok ? task - row * 12 : 0, c = 64 * h + 2 * i;
;             const float y0 = lo16(ya[u]) + lo16(yb[u]), y1 = hi16(ya[u]) + hi16(yb[u]);
;             float sm = y0 + y1;
; #pragma unroll
;             for (int o = 16; o > 0; o >>= 1) sm += __shfl_xor(sm, o);
;             const float mean = sm * (1.0f / 64.0f); const float d0 = y0 - mean, d1 = y1 - mean;
;             float vs = d0 * d0 + d1 * d1;
; #pragma unroll
;             for (int o = 16; o > 0; o >>= 1) vs += __shfl_xor(vs, o);
;             const float rs = rsqrtf(vs * (1.0f / 64.0f) + LNX_EPS);
;             const float x0 = bf2f(vr[u][0]), x1 = bf2f(vr[u][1]);
;             const float v0 = x0 + (0.5f * (bf2f(vr[u][2]) + bf2f(vr[u][4])) - x0) * P.cd_mu[1536 + c], v1 = x1 + (0.5f * (bf2f(vr[u][3]) + bf2f(vr[u][5])) - x1) * P.cd_mu[1536 + c + 1];
;             const float z0 = d0 * rs * P.cd_lnx_w[c] + P.cd_lnx_b[c] + bon[u] * v0, z1 = d1 * rs * P.cd_lnx_w[c + 1] + P.cd_lnx_b[c + 1] + bon[u] * v1;
;             const unsigned gg = *(const unsigned*)(Gt + (size_t)row * 768 + c);
;             if (ok) *(unsigned*)(Y + (size_t)row * DM + c) = pk2(z0 * lo16(gg), z1 * hi16(gg));
	v_add_f32_e32 v177, v180, v181
	v_lshlrev_b32_e32 v180, 16, v55
	v_lshlrev_b32_e32 v181, 16, v57
	v_add_f32_e32 v178, v180, v181
	v_and_b32_e32 v180, 0xffff0000, v55
	v_and_b32_e32 v181, 0xffff0000, v57
	v_add_f32_e32 v179, v180, v181
	v_add_f32_e32 v182, v176, v177
	v_add_f32_e32 v182, v182, v178
	v_add_f32_e32 v182, v182, v179
	s_nop 1
	v_add_f32_dpp v182, v182, v182 quad_perm:[1,0,3,2] row_mask:0xf bank_mask:0xf
	s_nop 1
	v_add_f32_dpp v182, v182, v182 quad_perm:[2,3,0,1] row_mask:0xf bank_mask:0xf
	s_nop 1
	v_add_f32_dpp v182, v182, v182 row_half_mirror row_mask:0xf bank_mask:0xf
	s_nop 1
	v_add_f32_dpp v182, v182, v182 row_mirror row_mask:0xf bank_mask:0xf
	s_nop 0
	v_mul_f32_e32 v183, 0x3c800000, v182
	v_sub_f32_e32 v176, v176, v183
	v_sub_f32_e32 v177, v177, v183
	v_sub_f32_e32 v178, v178, v183
	v_sub_f32_e32 v179, v179, v183
	v_mul_f32_e32 v182, v176, v176
	v_fmac_f32_e32 v182, v177, v177
	v_fmac_f32_e32 v182, v178, v178
	v_fmac_f32_e32 v182, v179, v179
	s_nop 1
	v_add_f32_dpp v182, v182, v182 quad_perm:[1,0,3,2] row_mask:0xf bank_mask:0xf
	s_nop 1
	v_add_f32_dpp v182, v182, v182 quad_perm:[2,3,0,1] row_mask:0xf bank_mask:0xf
	s_nop 1
	v_add_f32_dpp v182, v182, v182 row_half_mirror row_mask:0xf bank_mask:0xf
	s_nop 1
	v_add_f32_dpp v182, v182, v182 row_mirror row_mask:0xf bank_mask:0xf
	s_nop 0
	v_fmamk_f32 v184, v182, 0x3c800000, v39
	v_rsq_f32_e32 v184, v184
	v_and_b32_e32 v62, s12, v62
	v_and_b32_e32 v64, s13, v64
	v_lshlrev_b32_e32 v180, 16, v60
	v_lshlrev_b32_e32 v190, 16, v62
	v_lshlrev_b32_e32 v191, 16, v64
	v_add_f32_e32 v190, v190, v191
	v_fma_f32 v190, 0.5, v190, -v180
	v_fma_f32 v186, v190, v12, v180
	v_and_b32_e32 v180, 0xffff0000, v60
	v_and_b32_e32 v190, 0xffff0000, v62
	v_and_b32_e32 v191, 0xffff0000, v64
	v_add_f32_e32 v190, v190, v191
	v_fma_f32 v190, 0.5, v190, -v180
	v_fma_f32 v187, v190, v13, v180
	v_and_b32_e32 v63, s12, v63
	v_and_b32_e32 v65, s13, v65
	v_lshlrev_b32_e32 v180, 16, v61
	v_lshlrev_b32_e32 v190, 16, v63
	v_lshlrev_b32_e32 v191, 16, v65
	v_add_f32_e32 v190, v190, v191
	v_fma_f32 v190, 0.5, v190, -v180
	v_fma_f32 v188, v190, v14, v180
	v_and_b32_e32 v180, 0xffff0000, v61
	v_and_b32_e32 v190, 0xffff0000, v63
	v_and_b32_e32 v191, 0xffff0000, v65
	v_add_f32_e32 v190, v190, v191
	v_fma_f32 v190, 0.5, v190, -v180
	v_fma_f32 v189, v190, v15, v180
	v_add_f32_e32 v185, v66, v67
	v_mul_f32_e32 v176, v176, v184
	v_fma_f32 v176, v176, v16, v20
	v_fmac_f32_e32 v176, v185, v186
	v_mul_f32_e32 v177, v177, v184
	v_fma_f32 v177, v177, v17, v21
	v_fmac_f32_e32 v177, v185, v187
	v_mul_f32_e32 v178, v178, v184
	v_fma_f32 v178, v178, v18, v22
	v_fmac_f32_e32 v178, v185, v188
	v_mul_f32_e32 v179, v179, v184
	v_fma_f32 v179, v179, v19, v23
	v_fmac_f32_e32 v179, v185, v189
	v_lshlrev_b32_e32 v180, 16, v58
	v_mul_f32_e32 v176, v176, v180
	v_and_b32_e32 v180, 0xffff0000, v58
	v_mul_f32_e32 v177, v177, v180
	v_lshlrev_b32_e32 v180, 16, v59
	v_mul_f32_e32 v178, v178, v180
	v_and_b32_e32 v180, 0xffff0000, v59
	v_mul_f32_e32 v179, v179, v180
	v_cvt_pk_bf16_f32 v194, v176, v177
	v_cvt_pk_bf16_f32 v195, v178, v179
	global_store_dwordx2 v36, v[194:195], s[72:73] offset:512
	v_lshlrev_b32_e32 v180, 16, v68
	v_lshlrev_b32_e32 v181, 16, v70
	v_add_f32_e32 v176, v180, v181
	v_and_b32_e32 v180, 0xffff0000, v68
	v_and_b32_e32 v181, 0xffff0000, v70
	v_add_f32_e32 v177, v180, v181
	v_lshlrev_b32_e32 v180, 16, v69
	v_lshlrev_b32_e32 v181, 16, v71
	v_add_f32_e32 v178, v180, v181
	v_and_b32_e32 v180, 0xffff0000, v69
	v_and_b32_e32 v181, 0xffff0000, v71
	v_add_f32_e32 v179, v180, v181
	v_add_f32_e32 v182, v176, v177
	v_add_f32_e32 v182, v182, v178
	v_add_f32_e32 v182, v182, v179
	s_nop 1
	v_add_f32_dpp v182, v182, v182 quad_perm:[1,0,3,2] row_mask:0xf bank_mask:0xf
	s_nop 1
	v_add_f32_dpp v182, v182, v182 quad_perm:[2,3,0,1] row_mask:0xf bank_mask:0xf
	s_nop 1
	v_add_f32_dpp v182, v182, v182 row_half_mirror row_mask:0xf bank_mask:0xf
	s_nop 1
	v_add_f32_dpp v182, v182, v182 row_mirror row_mask:0xf bank_mask:0xf
	s_nop 0
	v_mul_f32_e32 v183, 0x3c800000, v182
	v_sub_f32_e32 v176, v176, v183
	v_sub_f32_e32 v177, v177, v183
	v_sub_f32_e32 v178, v178, v183
	v_sub_f32_e32 v179, v179, v183
	v_mul_f32_e32 v182, v176, v176
	v_fmac_f32_e32 v182, v177, v177
	v_fmac_f32_e32 v182, v178, v178
	v_fmac_f32_e32 v182, v179, v179
	s_nop 1
	v_add_f32_dpp v182, v182, v182 quad_perm:[1,0,3,2] row_mask:0xf bank_mask:0xf
	s_nop 1
	v_add_f32_dpp v182, v182, v182 quad_perm:[2,3,0,1] row_mask:0xf bank_mask:0xf
	s_nop 1
	v_add_f32_dpp v182, v182, v182 row_half_mirror row_mask:0xf bank_mask:0xf
	s_nop 1
	v_add_f32_dpp v182, v182, v182 row_mirror row_mask:0xf bank_mask:0xf
	s_nop 0
	v_fmamk_f32 v184, v182, 0x3c800000, v39
	v_rsq_f32_e32 v184, v184
	v_and_b32_e32 v76, s12, v76
	v_and_b32_e32 v78, s13, v78
	v_lshlrev_b32_e32 v180, 16, v74
	v_lshlrev_b32_e32 v190, 16, v76
	v_lshlrev_b32_e32 v191, 16, v78
	v_add_f32_e32 v190, v190, v191
	v_fma_f32 v190, 0.5, v190, -v180
	v_fma_f32 v186, v190, v24, v180
	v_and_b32_e32 v180, 0xffff0000, v74
	v_and_b32_e32 v190, 0xffff0000, v76
	v_and_b32_e32 v191, 0xffff0000, v78
	v_add_f32_e32 v190, v190, v191
	v_fma_f32 v190, 0.5, v190, -v180
	v_fma_f32 v187, v190, v25, v180
	v_and_b32_e32 v77, s12, v77
	v_and_b32_e32 v79, s13, v79
	v_lshlrev_b32_e32 v180, 16, v75
	v_lshlrev_b32_e32 v190, 16, v77
	v_lshlrev_b32_e32 v191, 16, v79
	v_add_f32_e32 v190, v190, v191
	v_fma_f32 v190, 0.5, v190, -v180
	v_fma_f32 v188, v190, v26, v180
	v_and_b32_e32 v180, 0xffff0000, v75
	v_and_b32_e32 v190, 0xffff0000, v77
	v_and_b32_e32 v191, 0xffff0000, v79
	v_add_f32_e32 v190, v190, v191
	v_fma_f32 v190, 0.5, v190, -v180
	v_fma_f32 v189, v190, v27, v180
	v_add_f32_e32 v185, v80, v81
	v_mul_f32_e32 v176, v176, v184
	v_fma_f32 v176, v176, v28, v32
	v_fmac_f32_e32 v176, v185, v186
	v_mul_f32_e32 v177, v177, v184
	v_fma_f32 v177, v177, v29, v33
	v_fmac_f32_e32 v177, v185, v187
	v_mul_f32_e32 v178, v178, v184
	v_fma_f32 v178, v178, v30, v34
	v_fmac_f32_e32 v178, v185, v188
	v_mul_f32_e32 v179, v179, v184
	v_fma_f32 v179, v179, v31, v35
	v_fmac_f32_e32 v179, v185, v189
	v_lshlrev_b32_e32 v180, 16, v72
	v_mul_f32_e32 v176, v176, v180
	v_and_b32_e32 v180, 0xffff0000, v72
	v_mul_f32_e32 v177, v177, v180
	v_lshlrev_b32_e32 v180, 16, v73
	v_mul_f32_e32 v178, v178, v180
	v_and_b32_e32 v180, 0xffff0000, v73
	v_mul_f32_e32 v179, v179, v180
	v_cvt_pk_bf16_f32 v196, v176, v177
	v_cvt_pk_bf16_f32 v197, v178, v179
	global_store_dwordx2 v36, v[196:197], s[72:73] offset:1024
	s_add_u32 s3, s3, 1
	s_waitcnt vmcnt(24)
; DI void zpass_phase(const Params& P) {
;     ...
;         for (int u = 0; u < 4; ++u) {
;             const int task = task0 + u * stride; const bool ok = task < NLAT * 12;
;             const int row = ok ? task / 12 : 0, h = ok ? task - row * 12 : 0, t = row & 8191, c = 64 * h + 2 * i;
;             ya[u] = *(const unsigned*)(YF + (size_t)row * 768 + c); yb[u] = *(const unsigned*)(YB + (size_t)row * 768 + c);
;             bon[u] = BON[(size_t)row * 12 + h] + BON[(size_t)NLAT * 12 + (size_t)row * 12 + h];
;             const bf16_t* pv = PL + (size_t)row * CDIN + 1536 + c;
;             const unsigned cur = *(const unsigned*)pv, prv = t > 0 ? *(const unsigned*)(pv - CDIN) : 0u, nxt = t + 1 < SEQ ? *(const unsigned*)(pv + CDIN) : 0u;
;             vr[u][0] = (unsigned short)(cur & 0xffff); vr[u][1] = (unsigned short)(cur >> 16); vr[u][2] = (unsigned short)(prv & 0xffff); vr[u][3] = (unsigned short)(prv >> 16);
;             vr[u][4] = (unsigned short)(nxt & 0xffff); vr[u][5] = (unsigned short)(nxt >> 16);
;         }
; #pragma unroll
;         for (int u = 0; u < 4; ++u) {
;             const int task = task0 + u * stride; const bool ok = task < NLAT * 12;
;             const int row = ok ? task / 12 : 0, h = ok ? task - row * 12 : 0, c = 64 * h + 2 * i;
;             const float y0 = lo16(ya[u]) + lo16(yb[u]), y1 = hi16(ya[u]) + hi16(yb[u]);
;             float sm = y0 + y1;
; #pragma unroll
;             for (int o = 16; o > 0; o >>= 1) sm += __shfl_xor(sm, o);
;             const float mean = sm * (1.0f / 64.0f); const float d0 = y0 - mean, d1 = y1 - mean;
;             float vs = d0 * d0 + d1 * d1;
; #pragma unroll
;             for (int o = 16; o > 0; o >>= 1) vs += __shfl_xor(vs, o);
;             const float rs = rsqrtf(vs * (1.0f / 64.0f) + LNX_EPS);
;             const float x0 = bf2f(vr[u][0]), x1 = bf2f(vr[u][1]);
;             const float v0 = x0 + (0.5f * (bf2f(vr[u][2]) + bf2f(vr[u][4])) - x0) * P.cd_mu[1536 + c], v1 = x1 + (0.5f * (bf2f(vr[u][3]) + bf2f(vr[u][5])) - x1) * P.cd_mu[1536 + c + 1];
;             const float z0 = d0 * rs * P.cd_lnx_w[c] + P.cd_lnx_b[c] + bon[u] * v0, z1 = d1 * rs * P.cd_lnx_w[c + 1] + P.cd_lnx_b[c + 1] + bon[u] * v1;
;             const unsigned gg = *(const unsigned*)(Gt + (size_t)row * 768 + c);
;             if (ok) *(unsigned*)(Y + (size_t)row * DM + c) = pk2(z0 * lo16(gg), z1 * hi16(gg));
	s_sub_u32 s14, s4, 1
	s_add_u32 s6, s3, 2
	s_min_u32 s15, s6, s14
	s_mul_i32 s6, s15, 0x600
	s_add_u32 s72, s60, s6
	s_addc_u32 s73, s61, 0
	global_load_dwordx2 v[40:41], v36, s[72:73]
	global_load_dwordx2 v[54:55], v36, s[72:73] offset:512
	global_load_dwordx2 v[68:69], v36, s[72:73] offset:1024
	s_add_u32 s72, s62, s6
	s_addc_u32 s73, s63, 0
	global_load_dwordx2 v[42:43], v36, s[72:73]
	global_load_dwordx2 v[56:57], v36, s[72:73] offset:512
	global_load_dwordx2 v[70:71], v36, s[72:73] offset:1024
	s_add_u32 s72, s64, s6
	s_addc_u32 s73, s65, 0
	global_load_dwordx2 v[44:45], v36, s[72:73]
	global_load_dwordx2 v[58:59], v36, s[72:73] offset:512
	global_load_dwordx2 v[72:73], v36, s[72:73] offset:1024
	s_mul_i32 s6, s15, 0x1700
	s_add_u32 s72, s66, s6
	s_addc_u32 s73, s67, 0
	global_load_dwordx2 v[46:47], v36, s[72:73]
	global_load_dwordx2 v[60:61], v36, s[72:73] offset:512
	global_load_dwordx2 v[74:75], v36, s[72:73] offset:1024
	s_and_b32 s14, s15, 0x1fff
	s_cmp_lg_u32 s14, 0
	s_cselect_b32 s14, 0x1700, 0
	s_sub_u32 s74, s72, s14
	s_subb_u32 s75, s73, 0
	global_load_dwordx2 v[48:49], v36, s[74:75]
	global_load_dwordx2 v[62:63], v36, s[74:75] offset:512
	global_load_dwordx2 v[76:77], v36, s[74:75] offset:1024
	s_and_b32 s14, s15, 0x1fff
	s_cmp_lg_u32 s14, 0x1fff
	s_cselect_b32 s14, 0x1700, 0
	s_add_u32 s74, s72, s14
	s_addc_u32 s75, s73, 0
	global_load_dwordx2 v[50:51], v36, s[74:75]
	global_load_dwordx2 v[64:65], v36, s[74:75] offset:512
	global_load_dwordx2 v[78:79], v36, s[74:75] offset:1024
	s_mul_i32 s6, s15, 48
	s_add_u32 s72, s68, s6
	s_addc_u32 s73, s69, 0
	global_load_dword v52, v37, s[72:73]
	global_load_dword v66, v37, s[72:73] offset:16
	global_load_dword v80, v37, s[72:73] offset:32
	s_add_u32 s72, s70, s6
	s_addc_u32 s73, s71, 0
	global_load_dword v53, v37, s[72:73]
	global_load_dword v67, v37, s[72:73] offset:16
	global_load_dword v81, v37, s[72:73] offset:32
	s_and_b32 s14, s3, 0x1fff
	s_cmp_lg_u32 s14, 0
	s_cselect_b32 s12, -1, 0
	s_cmp_lg_u32 s14, 0x1fff
	s_cselect_b32 s13, -1, 0
	s_lshl_b32 s6, s3, 11
	s_add_u32 s72, s24, s6
	s_addc_u32 s73, s25, 0
	v_lshlrev_b32_e32 v180, 16, v84
	v_lshlrev_b32_e32 v181, 16, v86
	v_add_f32_e32 v176, v180, v181
	v_and_b32_e32 v180, 0xffff0000, v84
	v_and_b32_e32 v181, 0xffff0000, v86
	v_add_f32_e32 v177, v180, v181
	v_lshlrev_b32_e32 v180, 16, v85
	v_lshlrev_b32_e32 v181, 16, v87
	v_add_f32_e32 v178, v180, v181
	v_and_b32_e32 v180, 0xffff0000, v85
	v_and_b32_e32 v181, 0xffff0000, v87
	v_add_f32_e32 v179, v180, v181
	v_add_f32_e32 v182, v176, v177
	v_add_f32_e32 v182, v182, v178
	v_add_f32_e32 v182, v182, v179
	s_nop 1
	v_add_f32_dpp v182, v182, v182 quad_perm:[1,0,3,2] row_mask:0xf bank_mask:0xf
	s_nop 1
	v_add_f32_dpp v182, v182, v182 quad_perm:[2,3,0,1] row_mask:0xf bank_mask:0xf
	s_nop 1
	v_add_f32_dpp v182, v182, v182 row_half_mirror row_mask:0xf bank_mask:0xf
	s_nop 1
	v_add_f32_dpp v182, v182, v182 row_mirror row_mask:0xf bank_mask:0xf
	s_nop 0
	v_mul_f32_e32 v183, 0x3c800000, v182
	v_sub_f32_e32 v176, v176, v183
	v_sub_f32_e32 v177, v177, v183
	v_sub_f32_e32 v178, v178, v183
	v_sub_f32_e32 v179, v179, v183
	v_mul_f32_e32 v182, v176, v176
	v_fmac_f32_e32 v182, v177, v177
	v_fmac_f32_e32 v182, v178, v178
	v_fmac_f32_e32 v182, v179, v179
	s_nop 1
	v_add_f32_dpp v182, v182, v182 quad_perm:[1,0,3,2] row_mask:0xf bank_mask:0xf
	s_nop 1
	v_add_f32_dpp v182, v182, v182 quad_perm:[2,3,0,1] row_mask:0xf bank_mask:0xf
	s_nop 1
	v_add_f32_dpp v182, v182, v182 row_half_mirror row_mask:0xf bank_mask:0xf
	s_nop 1
	v_add_f32_dpp v182, v182, v182 row_mirror row_mask:0xf bank_mask:0xf
	s_nop 0
	v_fmamk_f32 v184, v182, 0x3c800000, v39
	v_rsq_f32_e32 v184, v184
	v_and_b32_e32 v92, s12, v92
	v_and_b32_e32 v94, s13, v94
	v_lshlrev_b32_e32 v180, 16, v90
	v_lshlrev_b32_e32 v190, 16, v92
	v_lshlrev_b32_e32 v191, 16, v94
	v_add_f32_e32 v190, v190, v191
	v_fma_f32 v190, 0.5, v190, -v180
	v_fma_f32 v186, v190, v0, v180
	v_and_b32_e32 v180, 0xffff0000, v90
	v_and_b32_e32 v190, 0xffff0000, v92
	v_and_b32_e32 v191, 0xffff0000, v94
	v_add_f32_e32 v190, v190, v191
	v_fma_f32 v190, 0.5, v190, -v180
	v_fma_f32 v187, v190, v1, v180
	v_and_b32_e32 v93, s12, v93
	v_and_b32_e32 v95, s13, v95
	v_lshlrev_b32_e32 v180, 16, v91
	v_lshlrev_b32_e32 v190, 16, v93
	v_lshlrev_b32_e32 v191, 16, v95
	v_add_f32_e32 v190, v190, v191
	v_fma_f32 v190, 0.5, v190, -v180
	v_fma_f32 v188, v190, v2, v180
	v_and_b32_e32 v180, 0xffff0000, v91
	v_and_b32_e32 v190, 0xffff0000, v93
	v_and_b32_e32 v191, 0xffff0000, v95
	v_add_f32_e32 v190, v190, v191
	v_fma_f32 v190, 0.5, v190, -v180
	v_fma_f32 v189, v190, v3, v180
	v_add_f32_e32 v185, v96, v97
	v_mul_f32_e32 v176, v176, v184
	v_fma_f32 v176, v176, v4, v8
	v_fmac_f32_e32 v176, v185, v186
	v_mul_f32_e32 v177, v177, v184
	v_fma_f32 v177, v177, v5, v9
	v_fmac_f32_e32 v177, v185, v187
	v_mul_f32_e32 v178, v178, v184
	v_fma_f32 v178, v178, v6, v10
	v_fmac_f32_e32 v178, v185, v188
	v_mul_f32_e32 v179, v179, v184
	v_fma_f32 v179, v179, v7, v11
	v_fmac_f32_e32 v179, v185, v189
	v_lshlrev_b32_e32 v180, 16, v88
	v_mul_f32_e32 v176, v176, v180
	v_and_b32_e32 v180, 0xffff0000, v88
	v_mul_f32_e32 v177, v177, v180
	v_lshlrev_b32_e32 v180, 16, v89
	v_mul_f32_e32 v178, v178, v180
	v_and_b32_e32 v180, 0xffff0000, v89
	v_mul_f32_e32 v179, v179, v180
	v_cvt_pk_bf16_f32 v192, v176, v177
	v_cvt_pk_bf16_f32 v193, v178, v179
	global_store_dwordx2 v36, v[192:193], s[72:73]
	v_lshlrev_b32_e32 v180, 16, v98
	v_lshlrev_b32_e32 v181, 16, v100
	v_add_f32_e32 v176, v180, v181
	v_and_b32_e32 v180, 0xffff0000, v98
	v_and_b32_e32 v181, 0xffff0000, v100
	v_add_f32_e32 v177, v180, v181
	v_lshlrev_b32_e32 v180, 16, v99
; DI float bf2f(bf16_t b) { return __uint_as_float(((unsigned)b) << 16); }
; DI unsigned pk2(float lo, float hi) { const f32x2 v = {lo, hi}; return __builtin_bit_cast(unsigned, __builtin_convertvector(v, bf16x2v)); }
; DI float lo16(unsigned u) { return __uint_as_float(u << 16); }
; DI float hi16(unsigned u) { return __uint_as_float(u & 0xffff0000u); }
; DI void zpass_phase(const Params& P) {
;     ...
;         for (int u = 0; u < 4; ++u) {
;             const int task = task0 + u * stride; const bool ok = task < NLAT * 12;
;             const int row = ok ? task / 12 : 0, h = ok ? task - row * 12 : 0, c = 64 * h + 2 * i;
;             const float y0 = lo16(ya[u]) + lo16(yb[u]), y1 = hi16(ya[u]) + hi16(yb[u]);
;             float sm = y0 + y1;
; #pragma unroll
;             for (int o = 16; o > 0; o >>= 1) sm += __shfl_xor(sm, o);
;             const float mean = sm * (1.0f / 64.0f); const float d0 = y0 - mean, d1 = y1 - mean;
;             float vs = d0 * d0 + d1 * d1;
; #pragma unroll
;             for (int o = 16; o > 0; o >>= 1) vs += __shfl_xor(vs, o);
;             const float rs = rsqrtf(vs * (1.0f / 64.0f) + LNX_EPS);
;             const float x0 = bf2f(vr[u][0]), x1 = bf2f(vr[u][1]);
;             const float v0 = x0 + (0.5f * (bf2f(vr[u][2]) + bf2f(vr[u][4])) - x0) * P.cd_mu[1536 + c], v1 = x1 + (0.5f * (bf2f(vr[u][3]) + bf2f(vr[u][5])) - x1) * P.cd_mu[1536 + c + 1];
;             const float z0 = d0 * rs * P.cd_lnx_w[c] + P.cd_lnx_b[c] + bon[u] * v0, z1 = d1 * rs * P.cd_lnx_w[c + 1] + P.cd_lnx_b[c + 1] + bon[u] * v1;
;             const unsigned gg = *(const unsigned*)(Gt + (size_t)row * 768 + c);
;             if (ok) *(unsigned*)(Y + (size_t)row * DM + c) = pk2(z0 * lo16(gg), z1 * hi16(gg));
	v_lshlrev_b32_e32 v181, 16, v101
	v_add_f32_e32 v178, v180, v181
	v_and_b32_e32 v180, 0xffff0000, v99
	v_and_b32_e32 v181, 0xffff0000, v101
	v_add_f32_e32 v179, v180, v181
	v_add_f32_e32 v182, v176, v177
	v_add_f32_e32 v182, v182, v178
	v_add_f32_e32 v182, v182, v179
	s_nop 1
	v_add_f32_dpp v182, v182, v182 quad_perm:[1,0,3,2] row_mask:0xf bank_mask:0xf
	s_nop 1
	v_add_f32_dpp v182, v182, v182 quad_perm:[2,3,0,1] row_mask:0xf bank_mask:0xf
	s_nop 1
	v_add_f32_dpp v182, v182, v182 row_half_mirror row_mask:0xf bank_mask:0xf
	s_nop 1
	v_add_f32_dpp v182, v182, v182 row_mirror row_mask:0xf bank_mask:0xf
	s_nop 0
	v_mul_f32_e32 v183, 0x3c800000, v182
	v_sub_f32_e32 v176, v176, v183
	v_sub_f32_e32 v177, v177, v183
	v_sub_f32_e32 v178, v178, v183
	v_sub_f32_e32 v179, v179, v183
	v_mul_f32_e32 v182, v176, v176
	v_fmac_f32_e32 v182, v177, v177
	v_fmac_f32_e32 v182, v178, v178
	v_fmac_f32_e32 v182, v179, v179
	s_nop 1
	v_add_f32_dpp v182, v182, v182 quad_perm:[1,0,3,2] row_mask:0xf bank_mask:0xf
	s_nop 1
	v_add_f32_dpp v182, v182, v182 quad_perm:[2,3,0,1] row_mask:0xf bank_mask:0xf
	s_nop 1
	v_add_f32_dpp v182, v182, v182 row_half_mirror row_mask:0xf bank_mask:0xf
	s_nop 1
	v_add_f32_dpp v182, v182, v182 row_mirror row_mask:0xf bank_mask:0xf
	s_nop 0
	v_fmamk_f32 v184, v182, 0x3c800000, v39
	v_rsq_f32_e32 v184, v184
	v_and_b32_e32 v106, s12, v106
	v_and_b32_e32 v108, s13, v108
	v_lshlrev_b32_e32 v180, 16, v104
	v_lshlrev_b32_e32 v190, 16, v106
	v_lshlrev_b32_e32 v191, 16, v108
	v_add_f32_e32 v190, v190, v191
	v_fma_f32 v190, 0.5, v190, -v180
	v_fma_f32 v186, v190, v12, v180
	v_and_b32_e32 v180, 0xffff0000, v104
	v_and_b32_e32 v190, 0xffff0000, v106
	v_and_b32_e32 v191, 0xffff0000, v108
	v_add_f32_e32 v190, v190, v191
	v_fma_f32 v190, 0.5, v190, -v180
	v_fma_f32 v187, v190, v13, v180
	v_and_b32_e32 v107, s12, v107
	v_and_b32_e32 v109, s13, v109
	v_lshlrev_b32_e32 v180, 16, v105
	v_lshlrev_b32_e32 v190, 16, v107
	v_lshlrev_b32_e32 v191, 16, v109
	v_add_f32_e32 v190, v190, v191
	v_fma_f32 v190, 0.5, v190, -v180
	v_fma_f32 v188, v190, v14, v180
	v_and_b32_e32 v180, 0xffff0000, v105
	v_and_b32_e32 v190, 0xffff0000, v107
	v_and_b32_e32 v191, 0xffff0000, v109
	v_add_f32_e32 v190, v190, v191
	v_fma_f32 v190, 0.5, v190, -v180
	v_fma_f32 v189, v190, v15, v180
	v_add_f32_e32 v185, v110, v111
	v_mul_f32_e32 v176, v176, v184
	v_fma_f32 v176, v176, v16, v20
	v_fmac_f32_e32 v176, v185, v186
	v_mul_f32_e32 v177, v177, v184
	v_fma_f32 v177, v177, v17, v21
	v_fmac_f32_e32 v177, v185, v187
	v_mul_f32_e32 v178, v178, v184
	v_fma_f32 v178, v178, v18, v22
	v_fmac_f32_e32 v178, v185, v188
	v_mul_f32_e32 v179, v179, v184
	v_fma_f32 v179, v179, v19, v23
	v_fmac_f32_e32 v179, v185, v189
	v_lshlrev_b32_e32 v180, 16, v102
	v_mul_f32_e32 v176, v176, v180
	v_and_b32_e32 v180, 0xffff0000, v102
	v_mul_f32_e32 v177, v177, v180
	v_lshlrev_b32_e32 v180, 16, v103
	v_mul_f32_e32 v178, v178, v180
	v_and_b32_e32 v180, 0xffff0000, v103
	v_mul_f32_e32 v179, v179, v180
	v_cvt_pk_bf16_f32 v194, v176, v177
	v_cvt_pk_bf16_f32 v195, v178, v179
	global_store_dwordx2 v36, v[194:195], s[72:73] offset:512
	v_lshlrev_b32_e32 v180, 16, v112
	v_lshlrev_b32_e32 v181, 16, v114
	v_add_f32_e32 v176, v180, v181
	v_and_b32_e32 v180, 0xffff0000, v112
	v_and_b32_e32 v181, 0xffff0000, v114
	v_add_f32_e32 v177, v180, v181
	v_lshlrev_b32_e32 v180, 16, v113
	v_lshlrev_b32_e32 v181, 16, v115
	v_add_f32_e32 v178, v180, v181
	v_and_b32_e32 v180, 0xffff0000, v113
	v_and_b32_e32 v181, 0xffff0000, v115
	v_add_f32_e32 v179, v180, v181
	v_add_f32_e32 v182, v176, v177
	v_add_f32_e32 v182, v182, v178
	v_add_f32_e32 v182, v182, v179
	s_nop 1
	v_add_f32_dpp v182, v182, v182 quad_perm:[1,0,3,2] row_mask:0xf bank_mask:0xf
	s_nop 1
	v_add_f32_dpp v182, v182, v182 quad_perm:[2,3,0,1] row_mask:0xf bank_mask:0xf
	s_nop 1
	v_add_f32_dpp v182, v182, v182 row_half_mirror row_mask:0xf bank_mask:0xf
	s_nop 1
	v_add_f32_dpp v182, v182, v182 row_mirror row_mask:0xf bank_mask:0xf
	s_nop 0
	v_mul_f32_e32 v183, 0x3c800000, v182
	v_sub_f32_e32 v176, v176, v183
	v_sub_f32_e32 v177, v177, v183
	v_sub_f32_e32 v178, v178, v183
	v_sub_f32_e32 v179, v179, v183
	v_mul_f32_e32 v182, v176, v176
	v_fmac_f32_e32 v182, v177, v177
	v_fmac_f32_e32 v182, v178, v178
	v_fmac_f32_e32 v182, v179, v179
	s_nop 1
	v_add_f32_dpp v182, v182, v182 quad_perm:[1,0,3,2] row_mask:0xf bank_mask:0xf
	s_nop 1
	v_add_f32_dpp v182, v182, v182 quad_perm:[2,3,0,1] row_mask:0xf bank_mask:0xf
	s_nop 1
	v_add_f32_dpp v182, v182, v182 row_half_mirror row_mask:0xf bank_mask:0xf
	s_nop 1
	v_add_f32_dpp v182, v182, v182 row_mirror row_mask:0xf bank_mask:0xf
	s_nop 0
	v_fmamk_f32 v184, v182, 0x3c800000, v39
	v_rsq_f32_e32 v184, v184
	v_and_b32_e32 v120, s12, v120
	v_and_b32_e32 v122, s13, v122
	v_lshlrev_b32_e32 v180, 16, v118
	v_lshlrev_b32_e32 v190, 16, v120
	v_lshlrev_b32_e32 v191, 16, v122
	v_add_f32_e32 v190, v190, v191
	v_fma_f32 v190, 0.5, v190, -v180
	v_fma_f32 v186, v190, v24, v180
	v_and_b32_e32 v180, 0xffff0000, v118
	v_and_b32_e32 v190, 0xffff0000, v120
	v_and_b32_e32 v191, 0xffff0000, v122
	v_add_f32_e32 v190, v190, v191
	v_fma_f32 v190, 0.5, v190, -v180
	v_fma_f32 v187, v190, v25, v180
	v_and_b32_e32 v121, s12, v121
	v_and_b32_e32 v123, s13, v123
	v_lshlrev_b32_e32 v180, 16, v119
	v_lshlrev_b32_e32 v190, 16, v121
	v_lshlrev_b32_e32 v191, 16, v123
	v_add_f32_e32 v190, v190, v191
	v_fma_f32 v190, 0.5, v190, -v180
	v_fma_f32 v188, v190, v26, v180
	v_and_b32_e32 v180, 0xffff0000, v119
	v_and_b32_e32 v190, 0xffff0000, v121
	v_and_b32_e32 v191, 0xffff0000, v123
	v_add_f32_e32 v190, v190, v191
	v_fma_f32 v190, 0.5, v190, -v180
	v_fma_f32 v189, v190, v27, v180
	v_add_f32_e32 v185, v124, v125
	v_mul_f32_e32 v176, v176, v184
	v_fma_f32 v176, v176, v28, v32
	v_fmac_f32_e32 v176, v185, v186
	v_mul_f32_e32 v177, v177, v184
	v_fma_f32 v177, v177, v29, v33
	v_fmac_f32_e32 v177, v185, v187
	v_mul_f32_e32 v178, v178, v184
	v_fma_f32 v178, v178, v30, v34
	v_fmac_f32_e32 v178, v185, v188
	v_mul_f32_e32 v179, v179, v184
	v_fma_f32 v179, v179, v31, v35
	v_fmac_f32_e32 v179, v185, v189
	v_lshlrev_b32_e32 v180, 16, v116
	v_mul_f32_e32 v176, v176, v180
	v_and_b32_e32 v180, 0xffff0000, v116
	v_mul_f32_e32 v177, v177, v180
	v_lshlrev_b32_e32 v180, 16, v117
	v_mul_f32_e32 v178, v178, v180
	v_and_b32_e32 v180, 0xffff0000, v117
	v_mul_f32_e32 v179, v179, v180
	v_cvt_pk_bf16_f32 v196, v176, v177
	v_cvt_pk_bf16_f32 v197, v178, v179
	global_store_dwordx2 v36, v[196:197], s[72:73] offset:1024
	s_add_u32 s3, s3, 1
